# packed-vs-scalar fp32: v_pk_* split into scalar pairs in odd in-proj / SB / odd out-proj and in gate-up (SwiGLU) / down epilogues
# speedup vs baseline: 1.0000x; 1.0000x over previous
;     ...
;   const int m0 = tm << 8, n0 = tn << 7;
;   const bf16_t* Ag = A + (size_t)m0 * lda;
;   const bf16_t* Bg = Bt + (size_t)n0 * ldb;
;   if (ssq) {
;     const f32x4* sp = (const f32x4*)(ssq + (size_t)(m0 + tid) * 16);
;     const f32x4 a = sp[0], b = sp[1], c = sp[2], d = sp[3];
;     const float tot = ((a.x + a.y) + (a.z + a.w)) + ((b.x + b.y) + (b.z + b.w)) + ((c.x + c.y) + (c.z + c.w)) + ((d.x + d.y) + (d.z + d.w));
;     sR[tid] = rsqrtf(tot * (1.f / DM) + 1e-6f);
;   }
;   __syncthreads();
;     ...
;   for (int t = blockIdx.x; t < ntiles; t += gridDim.x) {
;     const int xcd = t & 7, j = t >> 3;
;     const int grp = j / (8 * nN), jj = j % (8 * nN);
;     const int tm = xcd * band + grp * 8 + (jj & 7), tn = jj >> 3;
;     int tmN = -1, tnN = 0;
;     const int tN = t + (int)gridDim.x;
;     if (Epi::CHAIN && tN < ntiles) {
;       const int xN = tN & 7, jN = tN >> 3, gN = jN / (8 * nN), jjN = jN % (8 * nN);
;       tmN = xN * band + gN * 8 + (jjN & 7); tnN = jjN >> 3;
.LBB0_191:
	s_ashr_i32 s11, s10, 3
	s_mul_hi_i32 s13, s11, 0x2aaaaaab
	s_lshr_b32 s16, s13, 31
	s_ashr_i32 s39, s13, 5
	s_add_i32 s39, s39, s16
	s_mul_i32 s13, s39, 0xc0
	s_sub_i32 s16, s11, s13
	s_and_b32 s10, s10, 7
	s_add_i32 s10, s39, s10
	s_lshl_b32 s11, s16, 8
	s_lshl_b32 s10, s10, 11
	s_and_b32 s40, s11, 0x700
	s_waitcnt vmcnt(0)
	v_mov_b32_e32 v152, v242
	s_or_b32 s38, s10, s40
	s_cmp_gt_i32 s12, -1
	v_add_u32_e32 v0, s38, v152
	v_ashrrev_i32_e32 v1, 31, v0
	v_lshlrev_b64 v[0:1], 6, v[0:1]
	v_lshl_add_u64 v[12:13], s[2:3], 0, v[0:1]
	flat_load_dwordx4 v[0:3], v[12:13]
	flat_load_dwordx4 v[4:7], v[12:13] offset:16
	flat_load_dwordx4 v[8:11], v[12:13] offset:32
	s_nop 0
	flat_load_dwordx4 v[12:15], v[12:13] offset:48
	s_cselect_b64 s[10:11], -1, 0
	s_cmp_lt_i32 s12, 0
	s_waitcnt vmcnt(0) lgkmcnt(0)
	v_mov_b32_e32 v16, v1
	v_mov_b32_e32 v17, v2
	v_mov_b32_e32 v1, v3
	v_mov_b32_e32 v2, v5
	v_mov_b32_e32 v3, v6
	v_mov_b32_e32 v5, v7
	v_add_f32_e64 v0, v16, v0
	v_add_f32_e64 v1, v17, v1
	v_add_f32_e64 v2, v2, v4
	v_add_f32_e64 v3, v3, v5
	v_pk_add_f32 v[0:1], v[0:1], v[0:1] op_sel:[0,1] op_sel_hi:[1,0]
	v_pk_add_f32 v[2:3], v[2:3], v[2:3] op_sel:[0,1] op_sel_hi:[1,0]
	v_add_f32_e32 v4, v8, v9
	v_add_f32_e32 v6, v10, v11
	v_mov_b32_e32 v1, v12
	v_mov_b32_e32 v3, v13
	v_mov_b32_e32 v5, v14
	v_mov_b32_e32 v7, v15
	v_add_f32_e64 v0, v0, v2
	v_add_f32_e64 v1, v1, v3
	v_add_f32_e64 v2, v4, v6
	v_add_f32_e64 v3, v5, v7
	s_nop 0
	v_add_f32_e64 v0, v0, v2
	v_add_f32_e64 v1, v1, v3
	s_nop 0
	v_add_f32_e32 v0, v0, v1
	v_fmamk_f32 v0, v0, 0x3a800000, v240
	v_cmp_gt_f32_e32 vcc, s79, v0
	v_mul_f32_e32 v1, 0x4b800000, v0
	s_nop 0
	v_cndmask_b32_e32 v0, v0, v1, vcc
	v_rsq_f32_e32 v0, v0
	s_nop 0
	v_mul_f32_e32 v1, 0x45800000, v0
	v_cndmask_b32_e32 v0, v0, v1, vcc
	v_lshl_add_u32 v1, v152, 2, v210
	ds_write_b32 v1, v0
	s_waitcnt lgkmcnt(0)
	s_barrier
	s_cbranch_scc1 .LBB0_193
	s_lshl_b32 s13, s12, 8
	s_mul_i32 s12, s12, 0x88000
	s_mul_hi_u32 s13, s13, 0x880
	s_add_u32 s12, s26, s12
	s_addc_u32 s13, s27, s13
	s_branch .LBB0_194

; DI u32x2 pack4(float a, float b, float c, float d) { u32x2 w; w.x = pack2(a, b); w.y = pack2(c, d); return w; }
;   DI void operator()(const f32x16 (&acc)[4][2], bool vt, int row0, int col0, int r, int h, const float* sR, float* stage) const {
;     ...
;     } else {
;       const int hh = seg - 32;
; #pragma unroll
;       for (int mi = 0; mi < 4; ++mi) {
; #pragma unroll
;         for (int g = 0; g < 4; ++g) {
;           const f32x4 rv = *(const f32x4*)(sR + mi * 32 + 8 * g + 4 * h);
; #pragma unroll
;           for (int ni = 0; ni < 2; ++ni)
;             *(u32x2*)(st + (ni * 32 + r) * 40 + 8 * g + 4 * h) =
;                 pack4(acc[mi][ni][4 * g] * rv.x, acc[mi][ni][4 * g + 1] * rv.y, acc[mi][ni][4 * g + 2] * rv.z, acc[mi][ni][4 * g + 3] * rv.w);
;         }
;         flush_tr(st, VT + (size_t)(b * 16 + hh) * 64 * SP + sb + mi * 32, lane);
;       }
;     }
.LBB0_214:
	s_or_b64 exec, exec, s[22:23]
	s_mov_b64 s[14:15], s[10:11]
	v_mad_u64_u32 v[130:131], s[10:11], v157, s75, v[32:33]
	v_and_b32_e32 v32, 0xffffff80, v152
	v_add_u32_e32 v131, s38, v32
	v_lshl_add_u32 v135, v32, 2, v210
	v_ashrrev_i32_e32 v32, 6, v155
	v_ashrrev_i32_e32 v133, 12, v131
	v_and_b32_e32 v132, 0xf80, v131
	v_cmp_lt_i32_e32 vcc, 31, v32
	v_lshlrev_b32_e32 v134, 3, v156
	v_lshlrev_b32_e32 v133, 4, v133
	v_lshlrev_b32_e32 v131, 4, v154
	s_waitcnt vmcnt(0) lgkmcnt(0)
	s_barrier
	s_and_saveexec_b64 s[10:11], vcc
	s_xor_b64 s[10:11], exec, s[10:11]
	s_cbranch_execz .LBB0_216
	v_lshl_add_u32 v135, v156, 4, v135
	ds_read_b128 v[136:139], v135
	v_mul_u32_u24_e32 v141, 40, v154
	v_lshlrev_b32_e32 v141, 1, v141
	v_add3_u32 v134, v130, v134, v141
	s_movk_i32 s12, 0xffe0
	s_waitcnt lgkmcnt(0)
	v_mul_f32_e64 v114, v114, v136
	v_mul_f32_e64 v115, v115, v137
	v_mul_f32_e64 v116, v116, v138
	v_mul_f32_e64 v117, v117, v139
	v_mul_f32_e64 v98, v98, v136
	v_mul_f32_e64 v99, v99, v137
	v_mul_f32_e64 v100, v100, v138
	v_mul_f32_e64 v101, v101, v139
	v_cvt_pk_bf16_f32 v114, v114, v115
	v_cvt_pk_bf16_f32 v115, v116, v117
	v_cvt_pk_bf16_f32 v98, v98, v99
	v_cvt_pk_bf16_f32 v99, v100, v101
	ds_write_b64 v134, v[114:115]
	ds_write_b64 v134, v[98:99] offset:2560
	ds_read_b128 v[98:101], v135 offset:32
	v_add3_u32 v32, v133, v32, s12
	s_mov_b32 s12, 0x84000
	s_waitcnt lgkmcnt(0)
	v_mul_f32_e64 v114, v118, v98
	v_mul_f32_e64 v115, v119, v99
	v_mul_f32_e64 v116, v120, v100
	v_mul_f32_e64 v117, v121, v101
	v_mul_f32_e64 v98, v102, v98
	v_mul_f32_e64 v99, v103, v99
	v_mul_f32_e64 v100, v104, v100
	v_mul_f32_e64 v101, v105, v101
	v_cvt_pk_bf16_f32 v114, v114, v115
	v_cvt_pk_bf16_f32 v115, v116, v117
	v_cvt_pk_bf16_f32 v98, v98, v99
	v_cvt_pk_bf16_f32 v99, v100, v101
	ds_write_b64 v134, v[114:115] offset:16
	ds_write_b64 v134, v[98:99] offset:2576
	ds_read_b128 v[98:101], v135 offset:64
	v_lshrrev_b32_e32 v114, 2, v153
	s_waitcnt lgkmcnt(0)
	v_mul_f32_e64 v102, v122, v98
	v_mul_f32_e64 v103, v123, v99
	v_mul_f32_e64 v104, v124, v100
	v_mul_f32_e64 v105, v125, v101
	v_mul_f32_e64 v98, v106, v98
	v_mul_f32_e64 v99, v107, v99
	v_mul_f32_e64 v100, v108, v100
	v_mul_f32_e64 v101, v109, v101
	v_cvt_pk_bf16_f32 v102, v102, v103
	v_cvt_pk_bf16_f32 v103, v104, v105
	v_cvt_pk_bf16_f32 v98, v98, v99
	v_cvt_pk_bf16_f32 v99, v100, v101
	ds_write_b64 v134, v[102:103] offset:32
	ds_write_b64 v134, v[98:99] offset:2592
	ds_read_b128 v[98:101], v135 offset:96
	v_and_b32_e32 v104, 48, v131
	v_mul_u32_u24_e32 v102, 0x50, v114
	v_add3_u32 v108, v130, v104, v102
	v_mul_u32_u24_e32 v109, 0x1080, v114
	s_waitcnt lgkmcnt(0)
	v_mul_f32_e64 v102, v126, v98
	v_mul_f32_e64 v103, v127, v99
	v_mul_f32_e64 v106, v128, v100
	v_mul_f32_e64 v107, v129, v101
	v_mul_f32_e64 v98, v110, v98
	v_mul_f32_e64 v99, v111, v99
	v_mul_f32_e64 v100, v112, v100
	v_mul_f32_e64 v101, v113, v101
	v_cvt_pk_bf16_f32 v102, v102, v103
	v_cvt_pk_bf16_f32 v103, v106, v107
	v_cvt_pk_bf16_f32 v98, v98, v99
	v_cvt_pk_bf16_f32 v99, v100, v101
	ds_write_b64 v134, v[102:103] offset:48
	ds_write_b64 v134, v[98:99] offset:2608
	v_mov_b64_e32 v[98:99], s[4:5]
	ds_read_b128 v[100:103], v108
	v_mad_i64_i32 v[98:99], s[12:13], v32, s12, v[98:99]
	v_lshlrev_b32_e32 v32, 1, v132
	v_lshl_add_u64 v[98:99], v[98:99], 0, v[32:33]
	v_mov_b32_e32 v105, v33
	v_lshl_add_u64 v[98:99], v[98:99], 0, v[104:105]
	v_lshlrev_b32_e32 v32, 1, v109
	v_lshl_add_u64 v[98:99], v[98:99], 0, v[32:33]
	s_waitcnt lgkmcnt(0)
	flat_store_dwordx4 v[98:99], v[100:103]
	ds_read_b128 v[100:103], v108 offset:1280
	s_mov_b32 s12, 0x21000
	v_add_co_u32_e32 v104, vcc, s12, v98
	s_mov_b32 s12, 0x42000
	s_nop 0
	v_addc_co_u32_e32 v105, vcc, 0, v99, vcc
	s_waitcnt lgkmcnt(0)
	flat_store_dwordx4 v[104:105], v[100:103]
	ds_read_b128 v[100:103], v108 offset:2560
	v_add_co_u32_e32 v104, vcc, s12, v98
	s_mov_b32 s12, 0x63000
	s_nop 0
	v_addc_co_u32_e32 v105, vcc, 0, v99, vcc
	s_waitcnt lgkmcnt(0)
	flat_store_dwordx4 v[104:105], v[100:103]
	ds_read_b128 v[100:103], v108 offset:3840
	v_add_co_u32_e32 v104, vcc, s12, v98
	s_mov_b64 s[12:13], 0x21000
	s_nop 0
	v_addc_co_u32_e32 v105, vcc, 0, v99, vcc
	s_waitcnt lgkmcnt(0)
	flat_store_dwordx4 v[104:105], v[100:103]
	ds_read_b128 v[100:103], v135 offset:128
	s_waitcnt lgkmcnt(0)
	v_mul_f32_e64 v82, v82, v100
	v_mul_f32_e64 v83, v83, v101
	v_mul_f32_e64 v84, v84, v102
	v_mul_f32_e64 v85, v85, v103
	v_mul_f32_e64 v66, v66, v100
	v_mul_f32_e64 v67, v67, v101
	v_mul_f32_e64 v68, v68, v102
	v_mul_f32_e64 v69, v69, v103
	v_cvt_pk_bf16_f32 v82, v82, v83
	v_cvt_pk_bf16_f32 v83, v84, v85
	v_cvt_pk_bf16_f32 v66, v66, v67
	v_cvt_pk_bf16_f32 v67, v68, v69
	ds_write_b64 v134, v[82:83]
	ds_write_b64 v134, v[66:67] offset:2560
	ds_read_b128 v[66:69], v135 offset:160
	s_waitcnt lgkmcnt(0)
	v_mul_f32_e64 v82, v86, v66
	v_mul_f32_e64 v83, v87, v67
	v_mul_f32_e64 v84, v88, v68
	v_mul_f32_e64 v85, v89, v69
	v_mul_f32_e64 v66, v70, v66
	v_mul_f32_e64 v67, v71, v67
	v_mul_f32_e64 v68, v72, v68
	v_mul_f32_e64 v69, v73, v69
	v_cvt_pk_bf16_f32 v82, v82, v83
	v_cvt_pk_bf16_f32 v83, v84, v85
	v_cvt_pk_bf16_f32 v66, v66, v67
	v_cvt_pk_bf16_f32 v67, v68, v69
	ds_write_b64 v134, v[82:83] offset:16
	ds_write_b64 v134, v[66:67] offset:2576
	ds_read_b128 v[66:69], v135 offset:192
	s_waitcnt lgkmcnt(0)
	v_mul_f32_e64 v70, v90, v66
	v_mul_f32_e64 v71, v91, v67
	v_mul_f32_e64 v72, v92, v68
	v_mul_f32_e64 v73, v93, v69
	v_mul_f32_e64 v66, v74, v66
	v_mul_f32_e64 v67, v75, v67
	v_mul_f32_e64 v68, v76, v68
	v_mul_f32_e64 v69, v77, v69
	v_cvt_pk_bf16_f32 v70, v70, v71
	v_cvt_pk_bf16_f32 v71, v72, v73
	v_cvt_pk_bf16_f32 v66, v66, v67
	v_cvt_pk_bf16_f32 v67, v68, v69
	ds_write_b64 v134, v[70:71] offset:32
	ds_write_b64 v134, v[66:67] offset:2592
	ds_read_b128 v[66:69], v135 offset:224
	s_waitcnt lgkmcnt(0)
; DI u32x2 pack4(float a, float b, float c, float d) { u32x2 w; w.x = pack2(a, b); w.y = pack2(c, d); return w; }
;   DI void operator()(const f32x16 (&acc)[4][2], bool vt, int row0, int col0, int r, int h, const float* sR, float* stage) const {
;     ...
;     } else {
;       const int hh = seg - 32;
; #pragma unroll
;       for (int mi = 0; mi < 4; ++mi) {
; #pragma unroll
;         for (int g = 0; g < 4; ++g) {
;           const f32x4 rv = *(const f32x4*)(sR + mi * 32 + 8 * g + 4 * h);
; #pragma unroll
;           for (int ni = 0; ni < 2; ++ni)
;             *(u32x2*)(st + (ni * 32 + r) * 40 + 8 * g + 4 * h) =
;                 pack4(acc[mi][ni][4 * g] * rv.x, acc[mi][ni][4 * g + 1] * rv.y, acc[mi][ni][4 * g + 2] * rv.z, acc[mi][ni][4 * g + 3] * rv.w);
;         }
;         flush_tr(st, VT + (size_t)(b * 16 + hh) * 64 * SP + sb + mi * 32, lane);
;       }
;     }
	v_mul_f32_e64 v70, v94, v66
	v_mul_f32_e64 v71, v95, v67
	v_mul_f32_e64 v72, v96, v68
	v_mul_f32_e64 v73, v97, v69
	v_mul_f32_e64 v66, v78, v66
	v_mul_f32_e64 v67, v79, v67
	v_mul_f32_e64 v68, v80, v68
	v_mul_f32_e64 v69, v81, v69
	v_cvt_pk_bf16_f32 v70, v70, v71
	v_cvt_pk_bf16_f32 v71, v72, v73
	v_cvt_pk_bf16_f32 v66, v66, v67
	v_cvt_pk_bf16_f32 v67, v68, v69
	ds_write_b64 v134, v[70:71] offset:48
	ds_write_b64 v134, v[66:67] offset:2608
	ds_read_b128 v[66:69], v108
	v_lshl_add_u64 v[70:71], v[98:99], 0, s[12:13]
	s_mov_b64 s[12:13], 0x42000
	v_lshl_add_u64 v[72:73], v[98:99], 0, s[12:13]
	s_mov_b64 s[12:13], 0x63000
	s_waitcnt lgkmcnt(0)
	flat_store_dwordx4 v[98:99], v[66:69] offset:64
	ds_read_b128 v[66:69], v108 offset:1280
	v_lshl_add_u64 v[74:75], v[98:99], 0, s[12:13]
	s_waitcnt lgkmcnt(0)
	flat_store_dwordx4 v[70:71], v[66:69] offset:64
	ds_read_b128 v[66:69], v108 offset:2560
	s_waitcnt lgkmcnt(0)
	flat_store_dwordx4 v[72:73], v[66:69] offset:64
	ds_read_b128 v[66:69], v108 offset:3840
	s_waitcnt lgkmcnt(0)
	flat_store_dwordx4 v[74:75], v[66:69] offset:64
	ds_read_b128 v[66:69], v135 offset:256
	s_waitcnt lgkmcnt(0)
	v_mul_f32_e64 v50, v50, v66
	v_mul_f32_e64 v51, v51, v67
	v_mul_f32_e64 v52, v52, v68
	v_mul_f32_e64 v53, v53, v69
	v_mul_f32_e64 v34, v34, v66
	v_mul_f32_e64 v35, v35, v67
	v_mul_f32_e64 v36, v36, v68
	v_mul_f32_e64 v37, v37, v69
	v_cvt_pk_bf16_f32 v50, v50, v51
	v_cvt_pk_bf16_f32 v51, v52, v53
	v_cvt_pk_bf16_f32 v34, v34, v35
	v_cvt_pk_bf16_f32 v35, v36, v37
	ds_write_b64 v134, v[50:51]
	ds_write_b64 v134, v[34:35] offset:2560
	ds_read_b128 v[34:37], v135 offset:288
	s_waitcnt lgkmcnt(0)
	v_mul_f32_e64 v50, v54, v34
	v_mul_f32_e64 v51, v55, v35
	v_mul_f32_e64 v52, v56, v36
	v_mul_f32_e64 v53, v57, v37
	v_mul_f32_e64 v34, v38, v34
	v_mul_f32_e64 v35, v39, v35
	v_mul_f32_e64 v36, v40, v36
	v_mul_f32_e64 v37, v41, v37
	v_cvt_pk_bf16_f32 v50, v50, v51
	v_cvt_pk_bf16_f32 v51, v52, v53
	v_cvt_pk_bf16_f32 v34, v34, v35
	v_cvt_pk_bf16_f32 v35, v36, v37
	ds_write_b64 v134, v[50:51] offset:16
	ds_write_b64 v134, v[34:35] offset:2576
	ds_read_b128 v[34:37], v135 offset:320
	s_waitcnt lgkmcnt(0)
	v_mul_f32_e64 v38, v58, v34
	v_mul_f32_e64 v39, v59, v35
	v_mul_f32_e64 v40, v60, v36
	v_mul_f32_e64 v41, v61, v37
	v_mul_f32_e64 v34, v42, v34
	v_mul_f32_e64 v35, v43, v35
	v_mul_f32_e64 v36, v44, v36
	v_mul_f32_e64 v37, v45, v37
	v_cvt_pk_bf16_f32 v38, v38, v39
	v_cvt_pk_bf16_f32 v39, v40, v41
	v_cvt_pk_bf16_f32 v34, v34, v35
	v_cvt_pk_bf16_f32 v35, v36, v37
	ds_write_b64 v134, v[38:39] offset:32
	ds_write_b64 v134, v[34:35] offset:2592
	ds_read_b128 v[34:37], v135 offset:352
	s_waitcnt lgkmcnt(0)
	v_mul_f32_e64 v38, v62, v34
	v_mul_f32_e64 v39, v63, v35
	v_mul_f32_e64 v40, v64, v36
	v_mul_f32_e64 v41, v65, v37
	v_mul_f32_e64 v34, v46, v34
	v_mul_f32_e64 v35, v47, v35
	v_mul_f32_e64 v36, v48, v36
	v_mul_f32_e64 v37, v49, v37
	v_cvt_pk_bf16_f32 v38, v38, v39
	v_cvt_pk_bf16_f32 v39, v40, v41
	v_cvt_pk_bf16_f32 v34, v34, v35
	v_cvt_pk_bf16_f32 v35, v36, v37
	ds_write_b64 v134, v[38:39] offset:48
	ds_write_b64 v134, v[34:35] offset:2608
	ds_read_b128 v[34:37], v108
	s_waitcnt lgkmcnt(0)
	flat_store_dwordx4 v[98:99], v[34:37] offset:128
	ds_read_b128 v[34:37], v108 offset:1280
	s_waitcnt lgkmcnt(0)
	flat_store_dwordx4 v[70:71], v[34:37] offset:128
	ds_read_b128 v[34:37], v108 offset:2560
	s_waitcnt lgkmcnt(0)
	flat_store_dwordx4 v[72:73], v[34:37] offset:128
	ds_read_b128 v[34:37], v108 offset:3840
	s_waitcnt lgkmcnt(0)
	flat_store_dwordx4 v[74:75], v[34:37] offset:128
	ds_read_b128 v[34:37], v135 offset:384
	s_waitcnt lgkmcnt(0)
	v_mul_f32_e64 v16, v16, v34
	v_mul_f32_e64 v17, v17, v35
	v_mul_f32_e64 v18, v18, v36
	v_mul_f32_e64 v19, v19, v37
	v_mul_f32_e64 v0, v0, v34
	v_mul_f32_e64 v1, v1, v35
	v_mul_f32_e64 v2, v2, v36
	v_mul_f32_e64 v3, v3, v37
	v_cvt_pk_bf16_f32 v16, v16, v17
	v_cvt_pk_bf16_f32 v17, v18, v19
	v_cvt_pk_bf16_f32 v0, v0, v1
	v_cvt_pk_bf16_f32 v1, v2, v3
	ds_write_b64 v134, v[16:17]
	ds_write_b64 v134, v[0:1] offset:2560
	ds_read_b128 v[0:3], v135 offset:416
	s_waitcnt lgkmcnt(0)
	v_mul_f32_e64 v16, v20, v0
	v_mul_f32_e64 v17, v21, v1
	v_mul_f32_e64 v18, v22, v2
	v_mul_f32_e64 v19, v23, v3
	v_mul_f32_e64 v0, v4, v0
	v_mul_f32_e64 v1, v5, v1
	v_mul_f32_e64 v2, v6, v2
	v_mul_f32_e64 v3, v7, v3
	v_cvt_pk_bf16_f32 v16, v16, v17
	v_cvt_pk_bf16_f32 v17, v18, v19
	v_cvt_pk_bf16_f32 v0, v0, v1
	v_cvt_pk_bf16_f32 v1, v2, v3
	ds_write_b64 v134, v[16:17] offset:16
	ds_write_b64 v134, v[0:1] offset:2576
	ds_read_b128 v[0:3], v135 offset:448
	s_waitcnt lgkmcnt(0)
	v_mul_f32_e64 v4, v24, v0
	v_mul_f32_e64 v5, v25, v1
	v_mul_f32_e64 v6, v26, v2
	v_mul_f32_e64 v7, v27, v3
	v_mul_f32_e64 v0, v8, v0
	v_mul_f32_e64 v1, v9, v1
	v_mul_f32_e64 v2, v10, v2
	v_mul_f32_e64 v3, v11, v3
	v_cvt_pk_bf16_f32 v4, v4, v5
	v_cvt_pk_bf16_f32 v5, v6, v7
	v_cvt_pk_bf16_f32 v0, v0, v1
	v_cvt_pk_bf16_f32 v1, v2, v3
	ds_write_b64 v134, v[4:5] offset:32
	ds_write_b64 v134, v[0:1] offset:2592
	ds_read_b128 v[0:3], v135 offset:480
	s_waitcnt lgkmcnt(0)
	v_mul_f32_e64 v4, v28, v0
	v_mul_f32_e64 v5, v29, v1
	v_mul_f32_e64 v6, v30, v2
	v_mul_f32_e64 v7, v31, v3
	v_mul_f32_e64 v0, v12, v0
	v_mul_f32_e64 v1, v13, v1
	v_mul_f32_e64 v2, v14, v2
	v_mul_f32_e64 v3, v15, v3
	v_cvt_pk_bf16_f32 v4, v4, v5
	v_cvt_pk_bf16_f32 v5, v6, v7
	v_cvt_pk_bf16_f32 v0, v0, v1
	v_cvt_pk_bf16_f32 v1, v2, v3
	ds_write_b64 v134, v[4:5] offset:48
	ds_write_b64 v134, v[0:1] offset:2608
	ds_read_b128 v[0:3], v108
	s_waitcnt lgkmcnt(0)
	flat_store_dwordx4 v[98:99], v[0:3] offset:192
	ds_read_b128 v[0:3], v108 offset:1280
	s_waitcnt lgkmcnt(0)
	flat_store_dwordx4 v[70:71], v[0:3] offset:192
	ds_read_b128 v[0:3], v108 offset:2560
	s_waitcnt lgkmcnt(0)
	flat_store_dwordx4 v[72:73], v[0:3] offset:192
	ds_read_b128 v[0:3], v108 offset:3840
	s_waitcnt lgkmcnt(0)
	flat_store_dwordx4 v[74:75], v[0:3] offset:192
; DI u32x2 pack4(float a, float b, float c, float d) { u32x2 w; w.x = pack2(a, b); w.y = pack2(c, d); return w; }
;   DI void operator()(const f32x16 (&acc)[4][2], bool vt, int row0, int col0, int r, int h, const float* sR, float* stage) const {
;     ...
;     if (seg < 32) {
;       bf16_t* dst = seg < 16 ? Q : K; const int hh = seg & 15; const float sc = seg < 16 ? 0.125f : 1.f;
; #pragma unroll
;       for (int mi = 0; mi < 4; ++mi) {
;         const float rv = sR[mi * 32 + r] * sc;
; #pragma unroll
;         for (int ni = 0; ni < 2; ++ni)
; #pragma unroll
;           for (int g = 0; g < 4; ++g)
;             *(u32x2*)(st + r * 72 + ni * 32 + 8 * g + 4 * h) = pack4(acc[mi][ni][4 * g] * rv, acc[mi][ni][4 * g + 1] * rv, acc[mi][ni][4 * g + 2] * rv, acc[mi][ni][4 * g + 3] * rv);
;         flush_rows(st, dst + ((size_t)(b * 16 + hh) * S + sb + mi * 32) * 64, lane);
;       }
.LBB0_216:
	s_andn2_saveexec_b64 s[10:11], s[10:11]
	s_cbranch_execz .LBB0_188
	v_cmp_gt_i32_e32 vcc, 16, v32
	v_mov_b32_e32 v32, 0x3e000000
	v_mov_b32_e32 v136, 0x7ad6000
	v_cndmask_b32_e32 v141, 1.0, v32, vcc
	v_mov_b32_e32 v32, 0x9ad6000
	v_cndmask_b32_e32 v32, v32, v136, vcc
	v_lshl_add_u64 v[136:137], s[0:1], 0, v[32:33]
	v_mul_u32_u24_e32 v32, 0x90, v154
	v_lshl_add_u32 v143, v154, 2, v135
	v_add3_u32 v142, v130, v32, v134
	v_and_b32_e32 v32, 0x70, v131
	ds_read_b32 v131, v143
	v_lshrrev_b32_e32 v138, 6, v155
	v_and_or_b32 v138, v138, 15, v133
	v_lshrrev_b32_e32 v133, 3, v153
	v_lshl_add_u64 v[134:135], v[136:137], 0, v[32:33]
	v_mul_u32_u24_e32 v136, 0x90, v133
	v_add3_u32 v136, v130, v32, v136
	s_waitcnt lgkmcnt(0)
	v_mul_f32_e32 v32, v141, v131
	v_mul_f32_e64 v114, v114, v32
	v_mul_f32_e64 v115, v115, v32
	v_mul_f32_e64 v116, v116, v32
	v_mul_f32_e64 v117, v117, v32
	v_mul_f32_e64 v98, v98, v32
	v_mul_f32_e64 v99, v99, v32
	v_mul_f32_e64 v100, v100, v32
	v_mul_f32_e64 v101, v101, v32
	v_cvt_pk_bf16_f32 v114, v114, v115
	v_cvt_pk_bf16_f32 v115, v116, v117
	v_cvt_pk_bf16_f32 v98, v98, v99
	v_cvt_pk_bf16_f32 v99, v100, v101
	ds_write_b64 v142, v[114:115]
	v_mul_f32_e64 v114, v118, v32
	v_mul_f32_e64 v115, v119, v32
	v_mul_f32_e64 v116, v120, v32
	v_mul_f32_e64 v117, v121, v32
	ds_write_b64 v142, v[98:99] offset:64
	v_mul_f32_e64 v98, v102, v32
	v_mul_f32_e64 v99, v103, v32
	v_mul_f32_e64 v100, v104, v32
	v_mul_f32_e64 v101, v105, v32
	v_cvt_pk_bf16_f32 v114, v114, v115
	v_cvt_pk_bf16_f32 v115, v116, v117
	v_cvt_pk_bf16_f32 v98, v98, v99
	v_cvt_pk_bf16_f32 v99, v100, v101
	ds_write_b64 v142, v[114:115] offset:16
	v_mul_f32_e64 v114, v122, v32
	v_mul_f32_e64 v115, v123, v32
	v_mul_f32_e64 v116, v124, v32
	v_mul_f32_e64 v117, v125, v32
	ds_write_b64 v142, v[98:99] offset:80
	v_mul_f32_e64 v98, v106, v32
	v_mul_f32_e64 v99, v107, v32
	v_mul_f32_e64 v100, v108, v32
	v_mul_f32_e64 v101, v109, v32
	v_cvt_pk_bf16_f32 v114, v114, v115
	v_cvt_pk_bf16_f32 v115, v116, v117
	v_cvt_pk_bf16_f32 v98, v98, v99
	v_cvt_pk_bf16_f32 v99, v100, v101
	ds_write_b64 v142, v[114:115] offset:32
	v_mul_f32_e64 v114, v126, v32
	v_mul_f32_e64 v115, v127, v32
	v_mul_f32_e64 v116, v128, v32
	v_mul_f32_e64 v117, v129, v32
	ds_write_b64 v142, v[98:99] offset:96
	v_mul_f32_e64 v98, v110, v32
	v_mul_f32_e64 v99, v111, v32
	v_mul_f32_e64 v100, v112, v32
	v_mul_f32_e64 v101, v113, v32
	v_cvt_pk_bf16_f32 v114, v114, v115
	v_cvt_pk_bf16_f32 v115, v116, v117
	v_cvt_pk_bf16_f32 v98, v98, v99
	v_cvt_pk_bf16_f32 v99, v100, v101
	ds_write_b64 v142, v[114:115] offset:48
	ds_write_b64 v142, v[98:99] offset:112
	v_ashrrev_i32_e32 v139, 31, v138
	ds_read_b128 v[100:103], v136
	v_lshlrev_b64 v[98:99], 19, v[138:139]
	v_lshlrev_b32_e32 v32, 7, v132
	v_lshl_add_u64 v[98:99], v[134:135], 0, v[98:99]
	v_lshlrev_b32_e32 v130, 7, v133
	v_lshl_add_u64 v[98:99], v[98:99], 0, v[32:33]
	v_mov_b32_e32 v131, v33
	v_lshl_add_u64 v[104:105], v[98:99], 0, v[130:131]
	s_waitcnt lgkmcnt(0)
	flat_store_dwordx4 v[104:105], v[100:103]
	ds_read_b128 v[100:103], v136 offset:1152
	v_or_b32_e32 v32, 0x400, v130
	v_lshl_add_u64 v[104:105], v[98:99], 0, v[32:33]
	s_mov_b64 s[12:13], 0x1000
	s_waitcnt lgkmcnt(0)
	flat_store_dwordx4 v[104:105], v[100:103]
	ds_read_b128 v[102:105], v136 offset:2304
	s_nop 0
	v_or_b32_e32 v100, 0x800, v130
	v_mov_b32_e32 v101, v33
	v_lshl_add_u64 v[106:107], v[98:99], 0, v[100:101]
	s_waitcnt lgkmcnt(0)
	flat_store_dwordx4 v[106:107], v[102:105]
	ds_read_b128 v[104:107], v136 offset:3456
	s_nop 0
	v_or_b32_e32 v102, 0xc00, v130
	v_mov_b32_e32 v103, v33
	v_lshl_add_u64 v[108:109], v[98:99], 0, v[102:103]
	s_waitcnt lgkmcnt(0)
	flat_store_dwordx4 v[108:109], v[104:107]
	ds_read_b32 v104, v143 offset:128
	s_waitcnt lgkmcnt(0)
	v_mul_f32_e32 v104, v141, v104
	v_mul_f32_e64 v82, v82, v104
	v_mul_f32_e64 v83, v83, v104
	v_mul_f32_e64 v84, v84, v104
	v_mul_f32_e64 v85, v85, v104
	v_mul_f32_e64 v66, v66, v104
	v_mul_f32_e64 v67, v67, v104
	v_mul_f32_e64 v68, v68, v104
	v_mul_f32_e64 v69, v69, v104
	v_cvt_pk_bf16_f32 v82, v82, v83
	v_cvt_pk_bf16_f32 v83, v84, v85
	v_cvt_pk_bf16_f32 v66, v66, v67
	v_cvt_pk_bf16_f32 v67, v68, v69
	ds_write_b64 v142, v[82:83]
	v_mul_f32_e64 v82, v86, v104
	v_mul_f32_e64 v83, v87, v104
	v_mul_f32_e64 v84, v88, v104
	v_mul_f32_e64 v85, v89, v104
	ds_write_b64 v142, v[66:67] offset:64
	v_mul_f32_e64 v66, v70, v104
	v_mul_f32_e64 v67, v71, v104
	v_mul_f32_e64 v68, v72, v104
	v_mul_f32_e64 v69, v73, v104
	v_cvt_pk_bf16_f32 v82, v82, v83
	v_cvt_pk_bf16_f32 v83, v84, v85
	v_cvt_pk_bf16_f32 v66, v66, v67
	v_cvt_pk_bf16_f32 v67, v68, v69
	ds_write_b64 v142, v[82:83] offset:16
	v_mul_f32_e64 v82, v90, v104
	v_mul_f32_e64 v83, v91, v104
	v_mul_f32_e64 v84, v92, v104
	v_mul_f32_e64 v85, v93, v104
	ds_write_b64 v142, v[66:67] offset:80
	v_mul_f32_e64 v66, v74, v104
	v_mul_f32_e64 v67, v75, v104
	v_mul_f32_e64 v68, v76, v104
	v_mul_f32_e64 v69, v77, v104
	v_cvt_pk_bf16_f32 v82, v82, v83
	v_cvt_pk_bf16_f32 v83, v84, v85
	v_cvt_pk_bf16_f32 v66, v66, v67
	v_cvt_pk_bf16_f32 v67, v68, v69
	ds_write_b64 v142, v[82:83] offset:32
	v_mul_f32_e64 v82, v94, v104
	v_mul_f32_e64 v83, v95, v104
	v_mul_f32_e64 v84, v96, v104
	v_mul_f32_e64 v85, v97, v104
	ds_write_b64 v142, v[66:67] offset:96
	v_mul_f32_e64 v66, v78, v104
	v_mul_f32_e64 v67, v79, v104
	v_mul_f32_e64 v68, v80, v104
	v_mul_f32_e64 v69, v81, v104
	v_cvt_pk_bf16_f32 v82, v82, v83
	v_cvt_pk_bf16_f32 v83, v84, v85
	v_cvt_pk_bf16_f32 v66, v66, v67
	v_cvt_pk_bf16_f32 v67, v68, v69
	ds_write_b64 v142, v[82:83] offset:48
	ds_write_b64 v142, v[66:67] offset:112
	ds_read_b128 v[66:69], v136
	v_lshl_add_u64 v[70:71], v[98:99], 0, s[12:13]
	v_lshl_add_u64 v[72:73], v[70:71], 0, v[130:131]
	s_mov_b64 s[12:13], 0x2000
	s_waitcnt lgkmcnt(0)
; DI u32x2 pack4(float a, float b, float c, float d) { u32x2 w; w.x = pack2(a, b); w.y = pack2(c, d); return w; }
;   DI void operator()(const f32x16 (&acc)[4][2], bool vt, int row0, int col0, int r, int h, const float* sR, float* stage) const {
;     ...
;     if (seg < 32) {
;       bf16_t* dst = seg < 16 ? Q : K; const int hh = seg & 15; const float sc = seg < 16 ? 0.125f : 1.f;
; #pragma unroll
;       for (int mi = 0; mi < 4; ++mi) {
;         const float rv = sR[mi * 32 + r] * sc;
; #pragma unroll
;         for (int ni = 0; ni < 2; ++ni)
; #pragma unroll
;           for (int g = 0; g < 4; ++g)
;             *(u32x2*)(st + r * 72 + ni * 32 + 8 * g + 4 * h) = pack4(acc[mi][ni][4 * g] * rv, acc[mi][ni][4 * g + 1] * rv, acc[mi][ni][4 * g + 2] * rv, acc[mi][ni][4 * g + 3] * rv);
;         flush_rows(st, dst + ((size_t)(b * 16 + hh) * S + sb + mi * 32) * 64, lane);
;       }
	flat_store_dwordx4 v[72:73], v[66:69]
	ds_read_b128 v[66:69], v136 offset:1152
	v_lshl_add_u64 v[72:73], v[70:71], 0, v[32:33]
	s_waitcnt lgkmcnt(0)
	flat_store_dwordx4 v[72:73], v[66:69]
	ds_read_b128 v[66:69], v136 offset:2304
	v_lshl_add_u64 v[72:73], v[70:71], 0, v[100:101]
	v_lshl_add_u64 v[70:71], v[70:71], 0, v[102:103]
	s_waitcnt lgkmcnt(0)
	flat_store_dwordx4 v[72:73], v[66:69]
	ds_read_b128 v[66:69], v136 offset:3456
	s_waitcnt lgkmcnt(0)
	flat_store_dwordx4 v[70:71], v[66:69]
	ds_read_b32 v66, v143 offset:256
	s_waitcnt lgkmcnt(0)
	v_mul_f32_e32 v66, v141, v66
	v_mul_f32_e64 v50, v50, v66
	v_mul_f32_e64 v51, v51, v66
	v_mul_f32_e64 v52, v52, v66
	v_mul_f32_e64 v53, v53, v66
	v_mul_f32_e64 v34, v34, v66
	v_mul_f32_e64 v35, v35, v66
	v_mul_f32_e64 v36, v36, v66
	v_mul_f32_e64 v37, v37, v66
	v_cvt_pk_bf16_f32 v50, v50, v51
	v_cvt_pk_bf16_f32 v51, v52, v53
	v_cvt_pk_bf16_f32 v34, v34, v35
	v_cvt_pk_bf16_f32 v35, v36, v37
	ds_write_b64 v142, v[50:51]
	v_mul_f32_e64 v50, v54, v66
	v_mul_f32_e64 v51, v55, v66
	v_mul_f32_e64 v52, v56, v66
	v_mul_f32_e64 v53, v57, v66
	ds_write_b64 v142, v[34:35] offset:64
	v_mul_f32_e64 v34, v38, v66
	v_mul_f32_e64 v35, v39, v66
	v_mul_f32_e64 v36, v40, v66
	v_mul_f32_e64 v37, v41, v66
	v_cvt_pk_bf16_f32 v50, v50, v51
	v_cvt_pk_bf16_f32 v51, v52, v53
	v_cvt_pk_bf16_f32 v34, v34, v35
	v_cvt_pk_bf16_f32 v35, v36, v37
	ds_write_b64 v142, v[50:51] offset:16
	v_mul_f32_e64 v50, v58, v66
	v_mul_f32_e64 v51, v59, v66
	v_mul_f32_e64 v52, v60, v66
	v_mul_f32_e64 v53, v61, v66
	ds_write_b64 v142, v[34:35] offset:80
	v_mul_f32_e64 v34, v42, v66
	v_mul_f32_e64 v35, v43, v66
	v_mul_f32_e64 v36, v44, v66
	v_mul_f32_e64 v37, v45, v66
	v_cvt_pk_bf16_f32 v50, v50, v51
	v_cvt_pk_bf16_f32 v51, v52, v53
	v_cvt_pk_bf16_f32 v34, v34, v35
	v_cvt_pk_bf16_f32 v35, v36, v37
	ds_write_b64 v142, v[50:51] offset:32
	v_mul_f32_e64 v50, v62, v66
	v_mul_f32_e64 v51, v63, v66
	v_mul_f32_e64 v52, v64, v66
	v_mul_f32_e64 v53, v65, v66
	ds_write_b64 v142, v[34:35] offset:96
	v_mul_f32_e64 v34, v46, v66
	v_mul_f32_e64 v35, v47, v66
	v_mul_f32_e64 v36, v48, v66
	v_mul_f32_e64 v37, v49, v66
	v_cvt_pk_bf16_f32 v50, v50, v51
	v_cvt_pk_bf16_f32 v51, v52, v53
	v_cvt_pk_bf16_f32 v34, v34, v35
	v_cvt_pk_bf16_f32 v35, v36, v37
	ds_write_b64 v142, v[50:51] offset:48
	ds_write_b64 v142, v[34:35] offset:112
	ds_read_b128 v[34:37], v136
	v_lshl_add_u64 v[38:39], v[98:99], 0, s[12:13]
	v_lshl_add_u64 v[40:41], v[38:39], 0, v[130:131]
	s_mov_b64 s[12:13], 0x3000
	s_waitcnt lgkmcnt(0)
	flat_store_dwordx4 v[40:41], v[34:37]
	ds_read_b128 v[34:37], v136 offset:1152
	v_lshl_add_u64 v[40:41], v[38:39], 0, v[32:33]
	s_waitcnt lgkmcnt(0)
	flat_store_dwordx4 v[40:41], v[34:37]
	ds_read_b128 v[34:37], v136 offset:2304
	v_lshl_add_u64 v[40:41], v[38:39], 0, v[100:101]
	v_lshl_add_u64 v[38:39], v[38:39], 0, v[102:103]
	s_waitcnt lgkmcnt(0)
	flat_store_dwordx4 v[40:41], v[34:37]
	ds_read_b128 v[34:37], v136 offset:3456
	s_waitcnt lgkmcnt(0)
	flat_store_dwordx4 v[38:39], v[34:37]
	ds_read_b32 v34, v143 offset:384
	s_waitcnt lgkmcnt(0)
	v_mul_f32_e32 v34, v141, v34
	v_mul_f32_e64 v16, v16, v34
	v_mul_f32_e64 v17, v17, v34
	v_mul_f32_e64 v18, v18, v34
	v_mul_f32_e64 v19, v19, v34
	v_mul_f32_e64 v0, v0, v34
	v_mul_f32_e64 v1, v1, v34
	v_mul_f32_e64 v2, v2, v34
	v_mul_f32_e64 v3, v3, v34
	v_cvt_pk_bf16_f32 v16, v16, v17
	v_cvt_pk_bf16_f32 v17, v18, v19
	v_cvt_pk_bf16_f32 v0, v0, v1
	v_cvt_pk_bf16_f32 v1, v2, v3
	ds_write_b64 v142, v[16:17]
	v_mul_f32_e64 v16, v20, v34
	v_mul_f32_e64 v17, v21, v34
	v_mul_f32_e64 v18, v22, v34
	v_mul_f32_e64 v19, v23, v34
	ds_write_b64 v142, v[0:1] offset:64
	v_mul_f32_e64 v0, v4, v34
	v_mul_f32_e64 v1, v5, v34
	v_mul_f32_e64 v2, v6, v34
	v_mul_f32_e64 v3, v7, v34
	v_cvt_pk_bf16_f32 v16, v16, v17
	v_cvt_pk_bf16_f32 v17, v18, v19
	v_cvt_pk_bf16_f32 v0, v0, v1
	v_cvt_pk_bf16_f32 v1, v2, v3
	ds_write_b64 v142, v[16:17] offset:16
	v_mul_f32_e64 v16, v24, v34
	v_mul_f32_e64 v17, v25, v34
	v_mul_f32_e64 v18, v26, v34
	v_mul_f32_e64 v19, v27, v34
	ds_write_b64 v142, v[0:1] offset:80
	v_mul_f32_e64 v0, v8, v34
	v_mul_f32_e64 v1, v9, v34
	v_mul_f32_e64 v2, v10, v34
	v_mul_f32_e64 v3, v11, v34
	v_cvt_pk_bf16_f32 v16, v16, v17
	v_cvt_pk_bf16_f32 v17, v18, v19
	v_cvt_pk_bf16_f32 v0, v0, v1
	v_cvt_pk_bf16_f32 v1, v2, v3
	ds_write_b64 v142, v[16:17] offset:32
	v_mul_f32_e64 v16, v28, v34
	v_mul_f32_e64 v17, v29, v34
	v_mul_f32_e64 v18, v30, v34
	v_mul_f32_e64 v19, v31, v34
	ds_write_b64 v142, v[0:1] offset:96
	v_mul_f32_e64 v0, v12, v34
	v_mul_f32_e64 v1, v13, v34
	v_mul_f32_e64 v2, v14, v34
	v_mul_f32_e64 v3, v15, v34
	v_cvt_pk_bf16_f32 v16, v16, v17
	v_cvt_pk_bf16_f32 v17, v18, v19
	v_cvt_pk_bf16_f32 v0, v0, v1
	v_cvt_pk_bf16_f32 v1, v2, v3
	ds_write_b64 v142, v[16:17] offset:48
	ds_write_b64 v142, v[0:1] offset:112
	ds_read_b128 v[0:3], v136
	v_lshl_add_u64 v[4:5], v[98:99], 0, s[12:13]
	v_lshl_add_u64 v[6:7], v[4:5], 0, v[130:131]
	s_waitcnt lgkmcnt(0)
	flat_store_dwordx4 v[6:7], v[0:3]
	ds_read_b128 v[0:3], v136 offset:1152
	v_lshl_add_u64 v[6:7], v[4:5], 0, v[32:33]
	s_waitcnt lgkmcnt(0)
	flat_store_dwordx4 v[6:7], v[0:3]
	ds_read_b128 v[0:3], v136 offset:2304
	v_lshl_add_u64 v[6:7], v[4:5], 0, v[100:101]
	v_lshl_add_u64 v[4:5], v[4:5], 0, v[102:103]
	s_waitcnt lgkmcnt(0)
	flat_store_dwordx4 v[6:7], v[0:3]
	ds_read_b128 v[0:3], v136 offset:3456
	s_waitcnt lgkmcnt(0)
	flat_store_dwordx4 v[4:5], v[0:3]
	s_branch .LBB0_188

; DI u32x2 pack4(float a, float b, float c, float d) { u32x2 w; w.x = pack2(a, b); w.y = pack2(c, d); return w; }
;   DI void operator()(const f32x16 (&acc)[4][2], bool vt, int row0, int col0, int r, int h, const float* sR, float* stage) const {
;     ...
; #pragma unroll
;       for (int j = 0; j < 8; ++j) {
;         const int rr = j * 4 + lr;
;         f32x4 v = *(const f32x4*)(stage + rr * 68 + lc);
;         const size_t row = row0 + mi * 32 + rr, idx = row * DM + col0 + lc;
;         const f32x4 xin = *(const f32x4*)(rin + idx);
;         v += xin;
;         *(f32x4*)(out + idx) = v;
;         *(u32x2*)(xb + row * LDX + col0 + lc) = pack4(v.x, v.y, v.z, v.w);
;         float ss = (v.x * v.x + v.y * v.y) + (v.z * v.z + v.w * v.w);
;         ss += __shfl_xor(ss, 1); ss += __shfl_xor(ss, 2); ss += __shfl_xor(ss, 4); ss += __shfl_xor(ss, 8);
;         if ((lane & 15) == 0) ssq[row * 16 + (col0 >> 6)] = ss;
;       }
.LBB0_516:
	s_or_b64 exec, exec, s[8:9]
	v_or_b32_e32 v109, 4, v142
	v_or_b32_e32 v102, v132, v109
	v_ashrrev_i32_e32 v103, 31, v102
	s_waitcnt lgkmcnt(0)
	v_lshlrev_b64 v[110:111], 12, v[102:103]
	v_lshl_add_u64 v[118:119], v[98:99], 0, v[110:111]
	flat_load_dwordx4 v[110:113], v[118:119]
	v_mul_u32_u24_e32 v32, 0x110, v142
	v_add_u32_e32 v108, v32, v108
	ds_read_b128 v[114:117], v108 offset:1088
	s_waitcnt vmcnt(0) lgkmcnt(0)
	v_add_f32_e64 v112, v116, v112
	v_add_f32_e64 v113, v117, v113
	v_add_f32_e64 v110, v114, v110
	v_add_f32_e64 v111, v115, v111
	v_mul_f32_e32 v114, v113, v113
	v_mul_f32_e32 v32, v111, v111
	v_fmac_f32_e32 v32, v110, v110
	v_fmac_f32_e32 v114, v112, v112
	v_add_f32_e32 v32, v32, v114
	ds_bpermute_b32 v114, v106, v32
	flat_store_dwordx4 v[118:119], v[110:113]
	v_lshlrev_b32_e32 v116, 2, v134
	s_waitcnt lgkmcnt(0)
	v_add_f32_e32 v32, v32, v114
	ds_bpermute_b32 v115, v105, v32
	v_cvt_pk_bf16_f32 v114, v110, v111
	v_mov_b64_e32 v[110:111], s[2:3]
	s_waitcnt lgkmcnt(0)
	v_add_f32_e32 v32, v32, v115
	ds_bpermute_b32 v117, v104, v32
	v_cvt_pk_bf16_f32 v115, v112, v113
	v_mad_i64_i32 v[112:113], s[8:9], v102, s74, v[110:111]
	v_lshl_add_u64 v[112:113], v[130:131], 1, v[112:113]
	s_waitcnt lgkmcnt(0)
	v_add_f32_e32 v110, v32, v117
	ds_bpermute_b32 v111, v107, v110
	v_lshlrev_b32_e32 v32, 1, v116
	v_lshl_add_u64 v[112:113], v[112:113], 0, v[32:33]
	flat_store_dwordx2 v[112:113], v[114:115]
	s_and_saveexec_b64 s[8:9], vcc
	s_cbranch_execz .LBB0_518
	v_lshlrev_b64 v[102:103], 6, v[102:103]
	v_lshl_add_u64 v[102:103], s[4:5], 0, v[102:103]
	v_lshl_add_u64 v[102:103], v[100:101], 2, v[102:103]
	s_waitcnt lgkmcnt(0)
	v_add_f32_e32 v110, v110, v111
	flat_store_dword v[102:103], v110
.LBB0_518:
	s_or_b64 exec, exec, s[8:9]
	v_or_b32_e32 v110, 8, v142
	v_or_b32_e32 v102, v132, v110
	v_ashrrev_i32_e32 v103, 31, v102
	v_lshlrev_b64 v[112:113], 12, v[102:103]
	v_lshl_add_u64 v[120:121], v[98:99], 0, v[112:113]
	flat_load_dwordx4 v[112:115], v[120:121]
	ds_read_b128 v[116:119], v108 offset:2176
	s_waitcnt vmcnt(0) lgkmcnt(0)
	v_add_f32_e64 v114, v118, v114
	v_add_f32_e64 v115, v119, v115
	v_add_f32_e64 v112, v116, v112
	v_add_f32_e64 v113, v117, v113
	v_mul_f32_e32 v116, v115, v115
	v_mul_f32_e32 v111, v113, v113
	v_fmac_f32_e32 v111, v112, v112
	v_fmac_f32_e32 v116, v114, v114
	v_add_f32_e32 v111, v111, v116
	ds_bpermute_b32 v116, v106, v111
	flat_store_dwordx4 v[120:121], v[112:115]
	v_cvt_pk_bf16_f32 v118, v112, v113
	v_cvt_pk_bf16_f32 v119, v114, v115
	s_waitcnt lgkmcnt(0)
	v_add_f32_e32 v111, v111, v116
	ds_bpermute_b32 v116, v105, v111
	s_waitcnt lgkmcnt(0)
	v_add_f32_e32 v111, v111, v116
	ds_bpermute_b32 v122, v104, v111
	v_mov_b64_e32 v[116:117], s[2:3]
	v_mad_i64_i32 v[114:115], s[8:9], v102, s74, v[116:117]
	v_lshl_add_u64 v[114:115], v[130:131], 1, v[114:115]
	s_waitcnt lgkmcnt(0)
	v_add_f32_e32 v111, v111, v122
	ds_bpermute_b32 v112, v107, v111
	v_lshl_add_u64 v[114:115], v[114:115], 0, v[32:33]
	flat_store_dwordx2 v[114:115], v[118:119]
	s_and_saveexec_b64 s[8:9], vcc
	s_cbranch_execz .LBB0_520
	v_lshlrev_b64 v[102:103], 6, v[102:103]
	v_lshl_add_u64 v[102:103], s[4:5], 0, v[102:103]
	v_lshl_add_u64 v[102:103], v[100:101], 2, v[102:103]
	s_waitcnt lgkmcnt(0)
	v_add_f32_e32 v111, v111, v112
	flat_store_dword v[102:103], v111
.LBB0_520:
	s_or_b64 exec, exec, s[8:9]
	v_or_b32_e32 v111, 12, v142
	v_or_b32_e32 v102, v132, v111
	v_ashrrev_i32_e32 v103, 31, v102
	s_waitcnt lgkmcnt(0)
	v_lshlrev_b64 v[112:113], 12, v[102:103]
	v_lshl_add_u64 v[120:121], v[98:99], 0, v[112:113]
	flat_load_dwordx4 v[112:115], v[120:121]
	ds_read_b128 v[116:119], v108 offset:3264
	s_waitcnt vmcnt(0) lgkmcnt(0)
	v_add_f32_e64 v114, v118, v114
	v_add_f32_e64 v115, v119, v115
	v_add_f32_e64 v112, v116, v112
	v_add_f32_e64 v113, v117, v113
	v_mul_f32_e32 v117, v115, v115
	v_mul_f32_e32 v116, v113, v113
	v_fmac_f32_e32 v116, v112, v112
	v_fmac_f32_e32 v117, v114, v114
	v_add_f32_e32 v116, v116, v117
	ds_bpermute_b32 v117, v106, v116
	flat_store_dwordx4 v[120:121], v[112:115]
	v_cvt_pk_bf16_f32 v118, v112, v113
	v_cvt_pk_bf16_f32 v119, v114, v115
	s_waitcnt lgkmcnt(0)
	v_add_f32_e32 v116, v116, v117
	ds_bpermute_b32 v117, v105, v116
	s_waitcnt lgkmcnt(0)
	v_add_f32_e32 v122, v116, v117
	ds_bpermute_b32 v123, v104, v122
	v_mov_b64_e32 v[116:117], s[2:3]
	v_mad_i64_i32 v[114:115], s[8:9], v102, s74, v[116:117]
	v_lshl_add_u64 v[114:115], v[130:131], 1, v[114:115]
	s_waitcnt lgkmcnt(0)
	v_add_f32_e32 v112, v122, v123
	ds_bpermute_b32 v113, v107, v112
	v_lshl_add_u64 v[114:115], v[114:115], 0, v[32:33]
	flat_store_dwordx2 v[114:115], v[118:119]
	s_and_saveexec_b64 s[8:9], vcc
	s_cbranch_execz .LBB0_522
	v_lshlrev_b64 v[102:103], 6, v[102:103]
	v_lshl_add_u64 v[102:103], s[4:5], 0, v[102:103]
	v_lshl_add_u64 v[102:103], v[100:101], 2, v[102:103]
	s_waitcnt lgkmcnt(0)
	v_add_f32_e32 v112, v112, v113
	flat_store_dword v[102:103], v112
; DI u32x2 pack4(float a, float b, float c, float d) { u32x2 w; w.x = pack2(a, b); w.y = pack2(c, d); return w; }
;   DI void operator()(const f32x16 (&acc)[4][2], bool vt, int row0, int col0, int r, int h, const float* sR, float* stage) const {
;     ...
; #pragma unroll
;       for (int j = 0; j < 8; ++j) {
;         const int rr = j * 4 + lr;
;         f32x4 v = *(const f32x4*)(stage + rr * 68 + lc);
;         const size_t row = row0 + mi * 32 + rr, idx = row * DM + col0 + lc;
;         const f32x4 xin = *(const f32x4*)(rin + idx);
;         v += xin;
;         *(f32x4*)(out + idx) = v;
;         *(u32x2*)(xb + row * LDX + col0 + lc) = pack4(v.x, v.y, v.z, v.w);
;         float ss = (v.x * v.x + v.y * v.y) + (v.z * v.z + v.w * v.w);
;         ss += __shfl_xor(ss, 1); ss += __shfl_xor(ss, 2); ss += __shfl_xor(ss, 4); ss += __shfl_xor(ss, 8);
;         if ((lane & 15) == 0) ssq[row * 16 + (col0 >> 6)] = ss;
;       }
.LBB0_522:
	s_or_b64 exec, exec, s[8:9]
	v_or_b32_e32 v112, 16, v142
	v_or_b32_e32 v102, v132, v112
	v_ashrrev_i32_e32 v103, 31, v102
	v_lshlrev_b64 v[114:115], 12, v[102:103]
	v_lshl_add_u64 v[122:123], v[98:99], 0, v[114:115]
	flat_load_dwordx4 v[114:117], v[122:123]
	ds_read_b128 v[118:121], v108 offset:4352
	s_waitcnt vmcnt(0) lgkmcnt(0)
	v_add_f32_e64 v116, v120, v116
	v_add_f32_e64 v117, v121, v117
	v_add_f32_e64 v114, v118, v114
	v_add_f32_e64 v115, v119, v115
	v_mul_f32_e32 v118, v117, v117
	v_mul_f32_e32 v113, v115, v115
	v_fmac_f32_e32 v113, v114, v114
	v_fmac_f32_e32 v118, v116, v116
	v_add_f32_e32 v113, v113, v118
	ds_bpermute_b32 v118, v106, v113
	flat_store_dwordx4 v[122:123], v[114:117]
	v_cvt_pk_bf16_f32 v120, v114, v115
	v_cvt_pk_bf16_f32 v121, v116, v117
	s_waitcnt lgkmcnt(0)
	v_add_f32_e32 v113, v113, v118
	ds_bpermute_b32 v118, v105, v113
	s_waitcnt lgkmcnt(0)
	v_add_f32_e32 v113, v113, v118
	ds_bpermute_b32 v124, v104, v113
	v_mov_b64_e32 v[118:119], s[2:3]
	v_mad_i64_i32 v[116:117], s[8:9], v102, s74, v[118:119]
	v_lshl_add_u64 v[116:117], v[130:131], 1, v[116:117]
	s_waitcnt lgkmcnt(0)
	v_add_f32_e32 v113, v113, v124
	ds_bpermute_b32 v114, v107, v113
	v_lshl_add_u64 v[116:117], v[116:117], 0, v[32:33]
	flat_store_dwordx2 v[116:117], v[120:121]
	s_and_saveexec_b64 s[8:9], vcc
	s_cbranch_execz .LBB0_524
	v_lshlrev_b64 v[102:103], 6, v[102:103]
	v_lshl_add_u64 v[102:103], s[4:5], 0, v[102:103]
	v_lshl_add_u64 v[102:103], v[100:101], 2, v[102:103]
	s_waitcnt lgkmcnt(0)
	v_add_f32_e32 v113, v113, v114
	flat_store_dword v[102:103], v113
.LBB0_524:
	s_or_b64 exec, exec, s[8:9]
	v_or_b32_e32 v113, 20, v142
	v_or_b32_e32 v102, v132, v113
	v_ashrrev_i32_e32 v103, 31, v102
	s_waitcnt lgkmcnt(0)
	v_lshlrev_b64 v[114:115], 12, v[102:103]
	v_lshl_add_u64 v[122:123], v[98:99], 0, v[114:115]
	flat_load_dwordx4 v[114:117], v[122:123]
	ds_read_b128 v[118:121], v108 offset:5440
	s_waitcnt vmcnt(0) lgkmcnt(0)
	v_add_f32_e64 v116, v120, v116
	v_add_f32_e64 v117, v121, v117
	v_add_f32_e64 v114, v118, v114
	v_add_f32_e64 v115, v119, v115
	v_mul_f32_e32 v119, v117, v117
	v_mul_f32_e32 v118, v115, v115
	v_fmac_f32_e32 v118, v114, v114
	v_fmac_f32_e32 v119, v116, v116
	v_add_f32_e32 v118, v118, v119
	ds_bpermute_b32 v119, v106, v118
	flat_store_dwordx4 v[122:123], v[114:117]
	v_cvt_pk_bf16_f32 v120, v114, v115
	v_cvt_pk_bf16_f32 v121, v116, v117
	s_waitcnt lgkmcnt(0)
	v_add_f32_e32 v118, v118, v119
	ds_bpermute_b32 v119, v105, v118
	s_waitcnt lgkmcnt(0)
	v_add_f32_e32 v124, v118, v119
	ds_bpermute_b32 v125, v104, v124
	v_mov_b64_e32 v[118:119], s[2:3]
	v_mad_i64_i32 v[116:117], s[8:9], v102, s74, v[118:119]
	v_lshl_add_u64 v[116:117], v[130:131], 1, v[116:117]
	s_waitcnt lgkmcnt(0)
	v_add_f32_e32 v114, v124, v125
	ds_bpermute_b32 v115, v107, v114
	v_lshl_add_u64 v[116:117], v[116:117], 0, v[32:33]
	flat_store_dwordx2 v[116:117], v[120:121]
	s_and_saveexec_b64 s[8:9], vcc
	s_cbranch_execz .LBB0_526
	v_lshlrev_b64 v[102:103], 6, v[102:103]
	v_lshl_add_u64 v[102:103], s[4:5], 0, v[102:103]
	v_lshl_add_u64 v[102:103], v[100:101], 2, v[102:103]
	s_waitcnt lgkmcnt(0)
	v_add_f32_e32 v114, v114, v115
	flat_store_dword v[102:103], v114
.LBB0_526:
	s_or_b64 exec, exec, s[8:9]
	v_or_b32_e32 v114, 24, v142
	v_or_b32_e32 v102, v132, v114
	v_ashrrev_i32_e32 v103, 31, v102
	v_lshlrev_b64 v[116:117], 12, v[102:103]
	v_lshl_add_u64 v[124:125], v[98:99], 0, v[116:117]
	flat_load_dwordx4 v[116:119], v[124:125]
	ds_read_b128 v[120:123], v108 offset:6528
	s_waitcnt vmcnt(0) lgkmcnt(0)
	v_add_f32_e64 v118, v122, v118
	v_add_f32_e64 v119, v123, v119
	v_add_f32_e64 v116, v120, v116
	v_add_f32_e64 v117, v121, v117
	v_mul_f32_e32 v120, v119, v119
	v_mul_f32_e32 v115, v117, v117
	v_fmac_f32_e32 v115, v116, v116
	v_fmac_f32_e32 v120, v118, v118
	v_add_f32_e32 v115, v115, v120
	ds_bpermute_b32 v120, v106, v115
	flat_store_dwordx4 v[124:125], v[116:119]
	v_cvt_pk_bf16_f32 v122, v116, v117
	v_cvt_pk_bf16_f32 v123, v118, v119
	s_waitcnt lgkmcnt(0)
	v_add_f32_e32 v115, v115, v120
	ds_bpermute_b32 v120, v105, v115
	s_waitcnt lgkmcnt(0)
	v_add_f32_e32 v115, v115, v120
	ds_bpermute_b32 v126, v104, v115
	v_mov_b64_e32 v[120:121], s[2:3]
	v_mad_i64_i32 v[118:119], s[8:9], v102, s74, v[120:121]
	v_lshl_add_u64 v[118:119], v[130:131], 1, v[118:119]
	s_waitcnt lgkmcnt(0)
	v_add_f32_e32 v115, v115, v126
	ds_bpermute_b32 v116, v107, v115
	v_lshl_add_u64 v[118:119], v[118:119], 0, v[32:33]
	flat_store_dwordx2 v[118:119], v[122:123]
	s_and_saveexec_b64 s[8:9], vcc
	s_cbranch_execz .LBB0_528
	v_lshlrev_b64 v[102:103], 6, v[102:103]
	v_lshl_add_u64 v[102:103], s[4:5], 0, v[102:103]
	v_lshl_add_u64 v[102:103], v[100:101], 2, v[102:103]
	s_waitcnt lgkmcnt(0)
	v_add_f32_e32 v115, v115, v116
	flat_store_dword v[102:103], v115
.LBB0_528:
	s_or_b64 exec, exec, s[8:9]
	v_or_b32_e32 v115, 28, v142
	v_or_b32_e32 v102, v132, v115
	v_ashrrev_i32_e32 v103, 31, v102
	s_waitcnt lgkmcnt(0)
	v_lshlrev_b64 v[116:117], 12, v[102:103]
	v_lshl_add_u64 v[124:125], v[98:99], 0, v[116:117]
	flat_load_dwordx4 v[116:119], v[124:125]
	ds_read_b128 v[120:123], v108 offset:7616
	s_waitcnt vmcnt(0) lgkmcnt(0)
	v_add_f32_e64 v118, v122, v118
	v_add_f32_e64 v119, v123, v119
	v_add_f32_e64 v116, v120, v116
	v_add_f32_e64 v117, v121, v117
	v_mul_f32_e32 v121, v119, v119
	v_mul_f32_e32 v120, v117, v117
	v_fmac_f32_e32 v120, v116, v116
	v_fmac_f32_e32 v121, v118, v118
	v_add_f32_e32 v120, v120, v121
	ds_bpermute_b32 v121, v106, v120
	flat_store_dwordx4 v[124:125], v[116:119]
	v_cvt_pk_bf16_f32 v122, v116, v117
	v_cvt_pk_bf16_f32 v123, v118, v119
	s_waitcnt lgkmcnt(0)
	v_add_f32_e32 v120, v120, v121
	ds_bpermute_b32 v121, v105, v120
	s_waitcnt lgkmcnt(0)
	v_add_f32_e32 v126, v120, v121
	ds_bpermute_b32 v127, v104, v126
	v_mov_b64_e32 v[120:121], s[2:3]
	v_mad_i64_i32 v[118:119], s[8:9], v102, s74, v[120:121]
	v_lshl_add_u64 v[118:119], v[130:131], 1, v[118:119]
	s_waitcnt lgkmcnt(0)
	v_add_f32_e32 v116, v126, v127
	ds_bpermute_b32 v117, v107, v116
	v_lshl_add_u64 v[118:119], v[118:119], 0, v[32:33]
	flat_store_dwordx2 v[118:119], v[122:123]
	s_and_saveexec_b64 s[8:9], vcc
	s_cbranch_execz .LBB0_530
	v_lshlrev_b64 v[102:103], 6, v[102:103]
	v_lshl_add_u64 v[102:103], s[4:5], 0, v[102:103]
	v_lshl_add_u64 v[102:103], v[100:101], 2, v[102:103]
	s_waitcnt lgkmcnt(0)
	v_add_f32_e32 v116, v116, v117
	flat_store_dword v[102:103], v116
; DI u32x2 pack4(float a, float b, float c, float d) { u32x2 w; w.x = pack2(a, b); w.y = pack2(c, d); return w; }
;   DI void operator()(const f32x16 (&acc)[4][2], bool vt, int row0, int col0, int r, int h, const float* sR, float* stage) const {
;     ...
;     for (int mi = 0; mi < 4; ++mi) {
; #pragma unroll
;       for (int ni = 0; ni < 2; ++ni)
; #pragma unroll
;         for (int g = 0; g < 4; ++g)
;           *(f32x4*)(stage + r * 68 + ni * 32 + 8 * g + 4 * h) = (f32x4){acc[mi][ni][4 * g], acc[mi][ni][4 * g + 1], acc[mi][ni][4 * g + 2], acc[mi][ni][4 * g + 3]};
; #pragma unroll
;       for (int j = 0; j < 8; ++j) {
;         const int rr = j * 4 + lr;
;         f32x4 v = *(const f32x4*)(stage + rr * 68 + lc);
;         const size_t row = row0 + mi * 32 + rr, idx = row * DM + col0 + lc;
;         const f32x4 xin = *(const f32x4*)(rin + idx);
;         v += xin;
;         *(f32x4*)(out + idx) = v;
;         *(u32x2*)(xb + row * LDX + col0 + lc) = pack4(v.x, v.y, v.z, v.w);
;         float ss = (v.x * v.x + v.y * v.y) + (v.z * v.z + v.w * v.w);
;         ss += __shfl_xor(ss, 1); ss += __shfl_xor(ss, 2); ss += __shfl_xor(ss, 4); ss += __shfl_xor(ss, 8);
;         if ((lane & 15) == 0) ssq[row * 16 + (col0 >> 6)] = ss;
;       }
.LBB0_530:
	s_or_b64 exec, exec, s[8:9]
	ds_write_b128 v133, v[82:85]
	ds_write_b128 v133, v[86:89] offset:32
	ds_write_b128 v133, v[90:93] offset:64
	ds_write_b128 v133, v[94:97] offset:96
	ds_write_b128 v133, v[66:69] offset:128
	ds_write_b128 v133, v[70:73] offset:160
	ds_write_b128 v133, v[74:77] offset:192
	ds_write_b128 v133, v[78:81] offset:224
	v_or_b32_e32 v68, 32, v132
	v_or_b32_e32 v66, v68, v142
	v_ashrrev_i32_e32 v67, 31, v66
	v_lshlrev_b64 v[70:71], 12, v[66:67]
	v_lshl_add_u64 v[78:79], v[98:99], 0, v[70:71]
	flat_load_dwordx4 v[70:73], v[78:79]
	ds_read_b128 v[74:77], v108
	s_waitcnt vmcnt(0) lgkmcnt(0)
	v_add_f32_e64 v72, v76, v72
	v_add_f32_e64 v73, v77, v73
	v_add_f32_e64 v70, v74, v70
	v_add_f32_e64 v71, v75, v71
	v_mul_f32_e32 v74, v73, v73
	v_mul_f32_e32 v69, v71, v71
	v_fmac_f32_e32 v69, v70, v70
	v_fmac_f32_e32 v74, v72, v72
	v_add_f32_e32 v69, v69, v74
	ds_bpermute_b32 v74, v106, v69
	flat_store_dwordx4 v[78:79], v[70:73]
	v_cvt_pk_bf16_f32 v76, v70, v71
	v_cvt_pk_bf16_f32 v77, v72, v73
	s_waitcnt lgkmcnt(0)
	v_add_f32_e32 v69, v69, v74
	ds_bpermute_b32 v74, v105, v69
	s_waitcnt lgkmcnt(0)
	v_add_f32_e32 v69, v69, v74
	ds_bpermute_b32 v80, v104, v69
	v_mov_b64_e32 v[74:75], s[2:3]
	v_mad_i64_i32 v[72:73], s[8:9], v66, s74, v[74:75]
	v_lshl_add_u64 v[72:73], v[130:131], 1, v[72:73]
	s_waitcnt lgkmcnt(0)
	v_add_f32_e32 v69, v69, v80
	ds_bpermute_b32 v70, v107, v69
	v_lshl_add_u64 v[72:73], v[72:73], 0, v[32:33]
	flat_store_dwordx2 v[72:73], v[76:77]
	s_and_saveexec_b64 s[8:9], vcc
	s_cbranch_execz .LBB0_532
	v_lshlrev_b64 v[66:67], 6, v[66:67]
	v_lshl_add_u64 v[66:67], s[4:5], 0, v[66:67]
	v_lshl_add_u64 v[66:67], v[100:101], 2, v[66:67]
	s_waitcnt lgkmcnt(0)
	v_add_f32_e32 v69, v69, v70
	flat_store_dword v[66:67], v69
.LBB0_532:
	s_or_b64 exec, exec, s[8:9]
	v_or_b32_e32 v66, v68, v109
	v_ashrrev_i32_e32 v67, 31, v66
	s_waitcnt lgkmcnt(0)
	v_lshlrev_b64 v[70:71], 12, v[66:67]
	v_lshl_add_u64 v[78:79], v[98:99], 0, v[70:71]
	flat_load_dwordx4 v[70:73], v[78:79]
	ds_read_b128 v[74:77], v108 offset:1088
	s_waitcnt vmcnt(0) lgkmcnt(0)
	v_add_f32_e64 v72, v76, v72
	v_add_f32_e64 v73, v77, v73
	v_add_f32_e64 v70, v74, v70
	v_add_f32_e64 v71, v75, v71
	v_mul_f32_e32 v74, v73, v73
	v_mul_f32_e32 v69, v71, v71
	v_fmac_f32_e32 v69, v70, v70
	v_fmac_f32_e32 v74, v72, v72
	v_add_f32_e32 v69, v69, v74
	ds_bpermute_b32 v74, v106, v69
	flat_store_dwordx4 v[78:79], v[70:73]
	v_cvt_pk_bf16_f32 v76, v70, v71
	v_cvt_pk_bf16_f32 v77, v72, v73
	s_waitcnt lgkmcnt(0)
	v_add_f32_e32 v69, v69, v74
	ds_bpermute_b32 v74, v105, v69
	s_waitcnt lgkmcnt(0)
	v_add_f32_e32 v69, v69, v74
	ds_bpermute_b32 v80, v104, v69
	v_mov_b64_e32 v[74:75], s[2:3]
	v_mad_i64_i32 v[72:73], s[8:9], v66, s74, v[74:75]
	v_lshl_add_u64 v[72:73], v[130:131], 1, v[72:73]
	s_waitcnt lgkmcnt(0)
	v_add_f32_e32 v69, v69, v80
	ds_bpermute_b32 v70, v107, v69
	v_lshl_add_u64 v[72:73], v[72:73], 0, v[32:33]
	flat_store_dwordx2 v[72:73], v[76:77]
	s_and_saveexec_b64 s[8:9], vcc
	s_cbranch_execz .LBB0_534
	v_lshlrev_b64 v[66:67], 6, v[66:67]
	v_lshl_add_u64 v[66:67], s[4:5], 0, v[66:67]
	v_lshl_add_u64 v[66:67], v[100:101], 2, v[66:67]
	s_waitcnt lgkmcnt(0)
	v_add_f32_e32 v69, v69, v70
	flat_store_dword v[66:67], v69
.LBB0_534:
	s_or_b64 exec, exec, s[8:9]
	v_or_b32_e32 v66, v68, v110
	v_ashrrev_i32_e32 v67, 31, v66
	s_waitcnt lgkmcnt(0)
	v_lshlrev_b64 v[70:71], 12, v[66:67]
	v_lshl_add_u64 v[78:79], v[98:99], 0, v[70:71]
	flat_load_dwordx4 v[70:73], v[78:79]
	ds_read_b128 v[74:77], v108 offset:2176
	s_waitcnt vmcnt(0) lgkmcnt(0)
	v_add_f32_e64 v72, v76, v72
	v_add_f32_e64 v73, v77, v73
	v_add_f32_e64 v70, v74, v70
	v_add_f32_e64 v71, v75, v71
	v_mul_f32_e32 v74, v73, v73
	v_mul_f32_e32 v69, v71, v71
	v_fmac_f32_e32 v69, v70, v70
	v_fmac_f32_e32 v74, v72, v72
	v_add_f32_e32 v69, v69, v74
	ds_bpermute_b32 v74, v106, v69
	flat_store_dwordx4 v[78:79], v[70:73]
	v_cvt_pk_bf16_f32 v76, v70, v71
	v_cvt_pk_bf16_f32 v77, v72, v73
	s_waitcnt lgkmcnt(0)
	v_add_f32_e32 v69, v69, v74
	ds_bpermute_b32 v74, v105, v69
	s_waitcnt lgkmcnt(0)
	v_add_f32_e32 v69, v69, v74
	ds_bpermute_b32 v80, v104, v69
	v_mov_b64_e32 v[74:75], s[2:3]
	v_mad_i64_i32 v[72:73], s[8:9], v66, s74, v[74:75]
	v_lshl_add_u64 v[72:73], v[130:131], 1, v[72:73]
	s_waitcnt lgkmcnt(0)
	v_add_f32_e32 v69, v69, v80
	ds_bpermute_b32 v70, v107, v69
	v_lshl_add_u64 v[72:73], v[72:73], 0, v[32:33]
	flat_store_dwordx2 v[72:73], v[76:77]
	s_and_saveexec_b64 s[8:9], vcc
	s_cbranch_execz .LBB0_536
	v_lshlrev_b64 v[66:67], 6, v[66:67]
	v_lshl_add_u64 v[66:67], s[4:5], 0, v[66:67]
	v_lshl_add_u64 v[66:67], v[100:101], 2, v[66:67]
	s_waitcnt lgkmcnt(0)
	v_add_f32_e32 v69, v69, v70
	flat_store_dword v[66:67], v69
.LBB0_536:
	s_or_b64 exec, exec, s[8:9]
	v_or_b32_e32 v66, v68, v111
	v_ashrrev_i32_e32 v67, 31, v66
	s_waitcnt lgkmcnt(0)
	v_lshlrev_b64 v[70:71], 12, v[66:67]
	v_lshl_add_u64 v[78:79], v[98:99], 0, v[70:71]
	flat_load_dwordx4 v[70:73], v[78:79]
	ds_read_b128 v[74:77], v108 offset:3264
	s_waitcnt vmcnt(0) lgkmcnt(0)
	v_add_f32_e64 v72, v76, v72
	v_add_f32_e64 v73, v77, v73
	v_add_f32_e64 v70, v74, v70
	v_add_f32_e64 v71, v75, v71
	v_mul_f32_e32 v74, v73, v73
	v_mul_f32_e32 v69, v71, v71
	v_fmac_f32_e32 v69, v70, v70
	v_fmac_f32_e32 v74, v72, v72
	v_add_f32_e32 v69, v69, v74
	ds_bpermute_b32 v74, v106, v69
	flat_store_dwordx4 v[78:79], v[70:73]
	v_cvt_pk_bf16_f32 v76, v70, v71
	v_cvt_pk_bf16_f32 v77, v72, v73
	s_waitcnt lgkmcnt(0)
	v_add_f32_e32 v69, v69, v74
	ds_bpermute_b32 v74, v105, v69
	s_waitcnt lgkmcnt(0)
	v_add_f32_e32 v69, v69, v74
	ds_bpermute_b32 v80, v104, v69
	v_mov_b64_e32 v[74:75], s[2:3]
	v_mad_i64_i32 v[72:73], s[8:9], v66, s74, v[74:75]
	v_lshl_add_u64 v[72:73], v[130:131], 1, v[72:73]
	s_waitcnt lgkmcnt(0)
	v_add_f32_e32 v69, v69, v80
	ds_bpermute_b32 v70, v107, v69
	v_lshl_add_u64 v[72:73], v[72:73], 0, v[32:33]
	flat_store_dwordx2 v[72:73], v[76:77]
	s_and_saveexec_b64 s[8:9], vcc
	s_cbranch_execz .LBB0_538
	v_lshlrev_b64 v[66:67], 6, v[66:67]
	v_lshl_add_u64 v[66:67], s[4:5], 0, v[66:67]
	v_lshl_add_u64 v[66:67], v[100:101], 2, v[66:67]
	s_waitcnt lgkmcnt(0)
	v_add_f32_e32 v69, v69, v70
	flat_store_dword v[66:67], v69
; DI u32x2 pack4(float a, float b, float c, float d) { u32x2 w; w.x = pack2(a, b); w.y = pack2(c, d); return w; }
;   DI void operator()(const f32x16 (&acc)[4][2], bool vt, int row0, int col0, int r, int h, const float* sR, float* stage) const {
;     ...
; #pragma unroll
;       for (int j = 0; j < 8; ++j) {
;         const int rr = j * 4 + lr;
;         f32x4 v = *(const f32x4*)(stage + rr * 68 + lc);
;         const size_t row = row0 + mi * 32 + rr, idx = row * DM + col0 + lc;
;         const f32x4 xin = *(const f32x4*)(rin + idx);
;         v += xin;
;         *(f32x4*)(out + idx) = v;
;         *(u32x2*)(xb + row * LDX + col0 + lc) = pack4(v.x, v.y, v.z, v.w);
;         float ss = (v.x * v.x + v.y * v.y) + (v.z * v.z + v.w * v.w);
;         ss += __shfl_xor(ss, 1); ss += __shfl_xor(ss, 2); ss += __shfl_xor(ss, 4); ss += __shfl_xor(ss, 8);
;         if ((lane & 15) == 0) ssq[row * 16 + (col0 >> 6)] = ss;
;       }
.LBB0_538:
	s_or_b64 exec, exec, s[8:9]
	v_or_b32_e32 v66, v68, v112
	v_ashrrev_i32_e32 v67, 31, v66
	s_waitcnt lgkmcnt(0)
	v_lshlrev_b64 v[70:71], 12, v[66:67]
	v_lshl_add_u64 v[78:79], v[98:99], 0, v[70:71]
	flat_load_dwordx4 v[70:73], v[78:79]
	ds_read_b128 v[74:77], v108 offset:4352
	s_waitcnt vmcnt(0) lgkmcnt(0)
	v_add_f32_e64 v72, v76, v72
	v_add_f32_e64 v73, v77, v73
	v_add_f32_e64 v70, v74, v70
	v_add_f32_e64 v71, v75, v71
	v_mul_f32_e32 v74, v73, v73
	v_mul_f32_e32 v69, v71, v71
	v_fmac_f32_e32 v69, v70, v70
	v_fmac_f32_e32 v74, v72, v72
	v_add_f32_e32 v69, v69, v74
	ds_bpermute_b32 v74, v106, v69
	flat_store_dwordx4 v[78:79], v[70:73]
	v_cvt_pk_bf16_f32 v76, v70, v71
	v_cvt_pk_bf16_f32 v77, v72, v73
	s_waitcnt lgkmcnt(0)
	v_add_f32_e32 v69, v69, v74
	ds_bpermute_b32 v74, v105, v69
	s_waitcnt lgkmcnt(0)
	v_add_f32_e32 v69, v69, v74
	ds_bpermute_b32 v80, v104, v69
	v_mov_b64_e32 v[74:75], s[2:3]
	v_mad_i64_i32 v[72:73], s[8:9], v66, s74, v[74:75]
	v_lshl_add_u64 v[72:73], v[130:131], 1, v[72:73]
	s_waitcnt lgkmcnt(0)
	v_add_f32_e32 v69, v69, v80
	ds_bpermute_b32 v70, v107, v69
	v_lshl_add_u64 v[72:73], v[72:73], 0, v[32:33]
	flat_store_dwordx2 v[72:73], v[76:77]
	s_and_saveexec_b64 s[8:9], vcc
	s_cbranch_execz .LBB0_540
	v_lshlrev_b64 v[66:67], 6, v[66:67]
	v_lshl_add_u64 v[66:67], s[4:5], 0, v[66:67]
	v_lshl_add_u64 v[66:67], v[100:101], 2, v[66:67]
	s_waitcnt lgkmcnt(0)
	v_add_f32_e32 v69, v69, v70
	flat_store_dword v[66:67], v69
.LBB0_540:
	s_or_b64 exec, exec, s[8:9]
	v_or_b32_e32 v66, v68, v113
	v_ashrrev_i32_e32 v67, 31, v66
	s_waitcnt lgkmcnt(0)
	v_lshlrev_b64 v[70:71], 12, v[66:67]
	v_lshl_add_u64 v[78:79], v[98:99], 0, v[70:71]
	flat_load_dwordx4 v[70:73], v[78:79]
	ds_read_b128 v[74:77], v108 offset:5440
	s_waitcnt vmcnt(0) lgkmcnt(0)
	v_add_f32_e64 v72, v76, v72
	v_add_f32_e64 v73, v77, v73
	v_add_f32_e64 v70, v74, v70
	v_add_f32_e64 v71, v75, v71
	v_mul_f32_e32 v74, v73, v73
	v_mul_f32_e32 v69, v71, v71
	v_fmac_f32_e32 v69, v70, v70
	v_fmac_f32_e32 v74, v72, v72
	v_add_f32_e32 v69, v69, v74
	ds_bpermute_b32 v74, v106, v69
	flat_store_dwordx4 v[78:79], v[70:73]
	v_cvt_pk_bf16_f32 v76, v70, v71
	v_cvt_pk_bf16_f32 v77, v72, v73
	s_waitcnt lgkmcnt(0)
	v_add_f32_e32 v69, v69, v74
	ds_bpermute_b32 v74, v105, v69
	s_waitcnt lgkmcnt(0)
	v_add_f32_e32 v69, v69, v74
	ds_bpermute_b32 v80, v104, v69
	v_mov_b64_e32 v[74:75], s[2:3]
	v_mad_i64_i32 v[72:73], s[8:9], v66, s74, v[74:75]
	v_lshl_add_u64 v[72:73], v[130:131], 1, v[72:73]
	s_waitcnt lgkmcnt(0)
	v_add_f32_e32 v69, v69, v80
	ds_bpermute_b32 v70, v107, v69
	v_lshl_add_u64 v[72:73], v[72:73], 0, v[32:33]
	flat_store_dwordx2 v[72:73], v[76:77]
	s_and_saveexec_b64 s[8:9], vcc
	s_cbranch_execz .LBB0_542
	v_lshlrev_b64 v[66:67], 6, v[66:67]
	v_lshl_add_u64 v[66:67], s[4:5], 0, v[66:67]
	v_lshl_add_u64 v[66:67], v[100:101], 2, v[66:67]
	s_waitcnt lgkmcnt(0)
	v_add_f32_e32 v69, v69, v70
	flat_store_dword v[66:67], v69
.LBB0_542:
	s_or_b64 exec, exec, s[8:9]
	v_or_b32_e32 v66, v68, v114
	v_ashrrev_i32_e32 v67, 31, v66
	s_waitcnt lgkmcnt(0)
	v_lshlrev_b64 v[70:71], 12, v[66:67]
	v_lshl_add_u64 v[78:79], v[98:99], 0, v[70:71]
	flat_load_dwordx4 v[70:73], v[78:79]
	ds_read_b128 v[74:77], v108 offset:6528
	s_waitcnt vmcnt(0) lgkmcnt(0)
	v_add_f32_e64 v72, v76, v72
	v_add_f32_e64 v73, v77, v73
	v_add_f32_e64 v70, v74, v70
	v_add_f32_e64 v71, v75, v71
	v_mul_f32_e32 v74, v73, v73
	v_mul_f32_e32 v69, v71, v71
	v_fmac_f32_e32 v69, v70, v70
	v_fmac_f32_e32 v74, v72, v72
	v_add_f32_e32 v69, v69, v74
	ds_bpermute_b32 v74, v106, v69
	flat_store_dwordx4 v[78:79], v[70:73]
	v_cvt_pk_bf16_f32 v76, v70, v71
	v_cvt_pk_bf16_f32 v77, v72, v73
	s_waitcnt lgkmcnt(0)
	v_add_f32_e32 v69, v69, v74
	ds_bpermute_b32 v74, v105, v69
	s_waitcnt lgkmcnt(0)
	v_add_f32_e32 v69, v69, v74
	ds_bpermute_b32 v80, v104, v69
	v_mov_b64_e32 v[74:75], s[2:3]
	v_mad_i64_i32 v[72:73], s[8:9], v66, s74, v[74:75]
	v_lshl_add_u64 v[72:73], v[130:131], 1, v[72:73]
	s_waitcnt lgkmcnt(0)
	v_add_f32_e32 v69, v69, v80
	ds_bpermute_b32 v70, v107, v69
	v_lshl_add_u64 v[72:73], v[72:73], 0, v[32:33]
	flat_store_dwordx2 v[72:73], v[76:77]
	s_and_saveexec_b64 s[8:9], vcc
	s_cbranch_execz .LBB0_544
	v_lshlrev_b64 v[66:67], 6, v[66:67]
	v_lshl_add_u64 v[66:67], s[4:5], 0, v[66:67]
	v_lshl_add_u64 v[66:67], v[100:101], 2, v[66:67]
	s_waitcnt lgkmcnt(0)
	v_add_f32_e32 v69, v69, v70
	flat_store_dword v[66:67], v69
.LBB0_544:
	s_or_b64 exec, exec, s[8:9]
	v_or_b32_e32 v66, v68, v115
	v_ashrrev_i32_e32 v67, 31, v66
	v_lshlrev_b64 v[68:69], 12, v[66:67]
	v_lshl_add_u64 v[76:77], v[98:99], 0, v[68:69]
	s_waitcnt lgkmcnt(0)
	flat_load_dwordx4 v[68:71], v[76:77]
	ds_read_b128 v[72:75], v108 offset:7616
	s_waitcnt vmcnt(0) lgkmcnt(0)
	v_add_f32_e64 v70, v74, v70
	v_add_f32_e64 v71, v75, v71
	v_add_f32_e64 v68, v72, v68
	v_add_f32_e64 v69, v73, v69
	v_mul_f32_e32 v73, v71, v71
	v_mul_f32_e32 v72, v69, v69
	v_fmac_f32_e32 v72, v68, v68
	v_fmac_f32_e32 v73, v70, v70
	v_add_f32_e32 v72, v72, v73
	ds_bpermute_b32 v73, v106, v72
	flat_store_dwordx4 v[76:77], v[68:71]
	v_cvt_pk_bf16_f32 v74, v68, v69
	v_cvt_pk_bf16_f32 v75, v70, v71
	s_waitcnt lgkmcnt(0)
	v_add_f32_e32 v72, v72, v73
	ds_bpermute_b32 v73, v105, v72
	s_waitcnt lgkmcnt(0)
	v_add_f32_e32 v78, v72, v73
	ds_bpermute_b32 v79, v104, v78
	v_mov_b64_e32 v[72:73], s[2:3]
	v_mad_i64_i32 v[70:71], s[8:9], v66, s74, v[72:73]
	v_lshl_add_u64 v[70:71], v[130:131], 1, v[70:71]
	s_waitcnt lgkmcnt(0)
	v_add_f32_e32 v68, v78, v79
	ds_bpermute_b32 v69, v107, v68
	v_lshl_add_u64 v[70:71], v[70:71], 0, v[32:33]
	flat_store_dwordx2 v[70:71], v[74:75]
	s_and_saveexec_b64 s[8:9], vcc
	s_cbranch_execz .LBB0_546
	v_lshlrev_b64 v[66:67], 6, v[66:67]
	v_lshl_add_u64 v[66:67], s[4:5], 0, v[66:67]
	v_lshl_add_u64 v[66:67], v[100:101], 2, v[66:67]
	s_waitcnt lgkmcnt(0)
	v_add_f32_e32 v68, v68, v69
	flat_store_dword v[66:67], v68
; DI u32x2 pack4(float a, float b, float c, float d) { u32x2 w; w.x = pack2(a, b); w.y = pack2(c, d); return w; }
;   DI void operator()(const f32x16 (&acc)[4][2], bool vt, int row0, int col0, int r, int h, const float* sR, float* stage) const {
;     ...
;     for (int mi = 0; mi < 4; ++mi) {
; #pragma unroll
;       for (int ni = 0; ni < 2; ++ni)
; #pragma unroll
;         for (int g = 0; g < 4; ++g)
;           *(f32x4*)(stage + r * 68 + ni * 32 + 8 * g + 4 * h) = (f32x4){acc[mi][ni][4 * g], acc[mi][ni][4 * g + 1], acc[mi][ni][4 * g + 2], acc[mi][ni][4 * g + 3]};
; #pragma unroll
;       for (int j = 0; j < 8; ++j) {
;         const int rr = j * 4 + lr;
;         f32x4 v = *(const f32x4*)(stage + rr * 68 + lc);
;         const size_t row = row0 + mi * 32 + rr, idx = row * DM + col0 + lc;
;         const f32x4 xin = *(const f32x4*)(rin + idx);
;         v += xin;
;         *(f32x4*)(out + idx) = v;
;         *(u32x2*)(xb + row * LDX + col0 + lc) = pack4(v.x, v.y, v.z, v.w);
;         float ss = (v.x * v.x + v.y * v.y) + (v.z * v.z + v.w * v.w);
;         ss += __shfl_xor(ss, 1); ss += __shfl_xor(ss, 2); ss += __shfl_xor(ss, 4); ss += __shfl_xor(ss, 8);
;         if ((lane & 15) == 0) ssq[row * 16 + (col0 >> 6)] = ss;
;       }
.LBB0_546:
	s_or_b64 exec, exec, s[8:9]
	ds_write_b128 v133, v[50:53]
	ds_write_b128 v133, v[54:57] offset:32
	ds_write_b128 v133, v[58:61] offset:64
	ds_write_b128 v133, v[62:65] offset:96
	ds_write_b128 v133, v[34:37] offset:128
	ds_write_b128 v133, v[38:41] offset:160
	ds_write_b128 v133, v[42:45] offset:192
	ds_write_b128 v133, v[46:49] offset:224
	v_or_b32_e32 v36, 64, v132
	v_or_b32_e32 v34, v36, v142
	v_ashrrev_i32_e32 v35, 31, v34
	v_lshlrev_b64 v[38:39], 12, v[34:35]
	v_lshl_add_u64 v[46:47], v[98:99], 0, v[38:39]
	flat_load_dwordx4 v[38:41], v[46:47]
	ds_read_b128 v[42:45], v108
	s_waitcnt vmcnt(0) lgkmcnt(0)
	v_add_f32_e64 v40, v44, v40
	v_add_f32_e64 v41, v45, v41
	v_add_f32_e64 v38, v42, v38
	v_add_f32_e64 v39, v43, v39
	v_mul_f32_e32 v42, v41, v41
	v_mul_f32_e32 v37, v39, v39
	v_fmac_f32_e32 v37, v38, v38
	v_fmac_f32_e32 v42, v40, v40
	v_add_f32_e32 v37, v37, v42
	ds_bpermute_b32 v42, v106, v37
	flat_store_dwordx4 v[46:47], v[38:41]
	v_cvt_pk_bf16_f32 v44, v38, v39
	v_cvt_pk_bf16_f32 v45, v40, v41
	s_waitcnt lgkmcnt(0)
	v_add_f32_e32 v37, v37, v42
	ds_bpermute_b32 v42, v105, v37
	s_waitcnt lgkmcnt(0)
	v_add_f32_e32 v37, v37, v42
	ds_bpermute_b32 v48, v104, v37
	v_mov_b64_e32 v[42:43], s[2:3]
	v_mad_i64_i32 v[40:41], s[8:9], v34, s74, v[42:43]
	v_lshl_add_u64 v[40:41], v[130:131], 1, v[40:41]
	s_waitcnt lgkmcnt(0)
	v_add_f32_e32 v37, v37, v48
	ds_bpermute_b32 v38, v107, v37
	v_lshl_add_u64 v[40:41], v[40:41], 0, v[32:33]
	flat_store_dwordx2 v[40:41], v[44:45]
	s_and_saveexec_b64 s[8:9], vcc
	s_cbranch_execz .LBB0_548
	v_lshlrev_b64 v[34:35], 6, v[34:35]
	v_lshl_add_u64 v[34:35], s[4:5], 0, v[34:35]
	v_lshl_add_u64 v[34:35], v[100:101], 2, v[34:35]
	s_waitcnt lgkmcnt(0)
	v_add_f32_e32 v37, v37, v38
	flat_store_dword v[34:35], v37
.LBB0_548:
	s_or_b64 exec, exec, s[8:9]
	v_or_b32_e32 v34, v36, v109
	v_ashrrev_i32_e32 v35, 31, v34
	s_waitcnt lgkmcnt(0)
	v_lshlrev_b64 v[38:39], 12, v[34:35]
	v_lshl_add_u64 v[46:47], v[98:99], 0, v[38:39]
	flat_load_dwordx4 v[38:41], v[46:47]
	ds_read_b128 v[42:45], v108 offset:1088
	s_waitcnt vmcnt(0) lgkmcnt(0)
	v_add_f32_e64 v40, v44, v40
	v_add_f32_e64 v41, v45, v41
	v_add_f32_e64 v38, v42, v38
	v_add_f32_e64 v39, v43, v39
	v_mul_f32_e32 v42, v41, v41
	v_mul_f32_e32 v37, v39, v39
	v_fmac_f32_e32 v37, v38, v38
	v_fmac_f32_e32 v42, v40, v40
	v_add_f32_e32 v37, v37, v42
	ds_bpermute_b32 v42, v106, v37
	flat_store_dwordx4 v[46:47], v[38:41]
	v_cvt_pk_bf16_f32 v44, v38, v39
	v_cvt_pk_bf16_f32 v45, v40, v41
	s_waitcnt lgkmcnt(0)
	v_add_f32_e32 v37, v37, v42
	ds_bpermute_b32 v42, v105, v37
	s_waitcnt lgkmcnt(0)
	v_add_f32_e32 v37, v37, v42
	ds_bpermute_b32 v48, v104, v37
	v_mov_b64_e32 v[42:43], s[2:3]
	v_mad_i64_i32 v[40:41], s[8:9], v34, s74, v[42:43]
	v_lshl_add_u64 v[40:41], v[130:131], 1, v[40:41]
	s_waitcnt lgkmcnt(0)
	v_add_f32_e32 v37, v37, v48
	ds_bpermute_b32 v38, v107, v37
	v_lshl_add_u64 v[40:41], v[40:41], 0, v[32:33]
	flat_store_dwordx2 v[40:41], v[44:45]
	s_and_saveexec_b64 s[8:9], vcc
	s_cbranch_execz .LBB0_550
	v_lshlrev_b64 v[34:35], 6, v[34:35]
	v_lshl_add_u64 v[34:35], s[4:5], 0, v[34:35]
	v_lshl_add_u64 v[34:35], v[100:101], 2, v[34:35]
	s_waitcnt lgkmcnt(0)
	v_add_f32_e32 v37, v37, v38
	flat_store_dword v[34:35], v37
.LBB0_550:
	s_or_b64 exec, exec, s[8:9]
	v_or_b32_e32 v34, v36, v110
	v_ashrrev_i32_e32 v35, 31, v34
	s_waitcnt lgkmcnt(0)
	v_lshlrev_b64 v[38:39], 12, v[34:35]
	v_lshl_add_u64 v[46:47], v[98:99], 0, v[38:39]
	flat_load_dwordx4 v[38:41], v[46:47]
	ds_read_b128 v[42:45], v108 offset:2176
	s_waitcnt vmcnt(0) lgkmcnt(0)
	v_add_f32_e64 v40, v44, v40
	v_add_f32_e64 v41, v45, v41
	v_add_f32_e64 v38, v42, v38
	v_add_f32_e64 v39, v43, v39
	v_mul_f32_e32 v42, v41, v41
	v_mul_f32_e32 v37, v39, v39
	v_fmac_f32_e32 v37, v38, v38
	v_fmac_f32_e32 v42, v40, v40
	v_add_f32_e32 v37, v37, v42
	ds_bpermute_b32 v42, v106, v37
	flat_store_dwordx4 v[46:47], v[38:41]
	v_cvt_pk_bf16_f32 v44, v38, v39
	v_cvt_pk_bf16_f32 v45, v40, v41
	s_waitcnt lgkmcnt(0)
	v_add_f32_e32 v37, v37, v42
	ds_bpermute_b32 v42, v105, v37
	s_waitcnt lgkmcnt(0)
	v_add_f32_e32 v37, v37, v42
	ds_bpermute_b32 v48, v104, v37
	v_mov_b64_e32 v[42:43], s[2:3]
	v_mad_i64_i32 v[40:41], s[8:9], v34, s74, v[42:43]
	v_lshl_add_u64 v[40:41], v[130:131], 1, v[40:41]
	s_waitcnt lgkmcnt(0)
	v_add_f32_e32 v37, v37, v48
	ds_bpermute_b32 v38, v107, v37
	v_lshl_add_u64 v[40:41], v[40:41], 0, v[32:33]
	flat_store_dwordx2 v[40:41], v[44:45]
	s_and_saveexec_b64 s[8:9], vcc
	s_cbranch_execz .LBB0_552
	v_lshlrev_b64 v[34:35], 6, v[34:35]
	v_lshl_add_u64 v[34:35], s[4:5], 0, v[34:35]
	v_lshl_add_u64 v[34:35], v[100:101], 2, v[34:35]
	s_waitcnt lgkmcnt(0)
	v_add_f32_e32 v37, v37, v38
	flat_store_dword v[34:35], v37
.LBB0_552:
	s_or_b64 exec, exec, s[8:9]
	v_or_b32_e32 v34, v36, v111
	v_ashrrev_i32_e32 v35, 31, v34
	s_waitcnt lgkmcnt(0)
	v_lshlrev_b64 v[38:39], 12, v[34:35]
	v_lshl_add_u64 v[46:47], v[98:99], 0, v[38:39]
	flat_load_dwordx4 v[38:41], v[46:47]
	ds_read_b128 v[42:45], v108 offset:3264
	s_waitcnt vmcnt(0) lgkmcnt(0)
	v_add_f32_e64 v40, v44, v40
	v_add_f32_e64 v41, v45, v41
	v_add_f32_e64 v38, v42, v38
	v_add_f32_e64 v39, v43, v39
	v_mul_f32_e32 v42, v41, v41
	v_mul_f32_e32 v37, v39, v39
	v_fmac_f32_e32 v37, v38, v38
	v_fmac_f32_e32 v42, v40, v40
	v_add_f32_e32 v37, v37, v42
	ds_bpermute_b32 v42, v106, v37
	flat_store_dwordx4 v[46:47], v[38:41]
	v_cvt_pk_bf16_f32 v44, v38, v39
	v_cvt_pk_bf16_f32 v45, v40, v41
	s_waitcnt lgkmcnt(0)
	v_add_f32_e32 v37, v37, v42
	ds_bpermute_b32 v42, v105, v37
	s_waitcnt lgkmcnt(0)
	v_add_f32_e32 v37, v37, v42
	ds_bpermute_b32 v48, v104, v37
	v_mov_b64_e32 v[42:43], s[2:3]
	v_mad_i64_i32 v[40:41], s[8:9], v34, s74, v[42:43]
	v_lshl_add_u64 v[40:41], v[130:131], 1, v[40:41]
	s_waitcnt lgkmcnt(0)
	v_add_f32_e32 v37, v37, v48
	ds_bpermute_b32 v38, v107, v37
	v_lshl_add_u64 v[40:41], v[40:41], 0, v[32:33]
	flat_store_dwordx2 v[40:41], v[44:45]
	s_and_saveexec_b64 s[8:9], vcc
	s_cbranch_execz .LBB0_554
	v_lshlrev_b64 v[34:35], 6, v[34:35]
	v_lshl_add_u64 v[34:35], s[4:5], 0, v[34:35]
	v_lshl_add_u64 v[34:35], v[100:101], 2, v[34:35]
	s_waitcnt lgkmcnt(0)
	v_add_f32_e32 v37, v37, v38
	flat_store_dword v[34:35], v37
; DI u32x2 pack4(float a, float b, float c, float d) { u32x2 w; w.x = pack2(a, b); w.y = pack2(c, d); return w; }
;   DI void operator()(const f32x16 (&acc)[4][2], bool vt, int row0, int col0, int r, int h, const float* sR, float* stage) const {
;     ...
; #pragma unroll
;       for (int j = 0; j < 8; ++j) {
;         const int rr = j * 4 + lr;
;         f32x4 v = *(const f32x4*)(stage + rr * 68 + lc);
;         const size_t row = row0 + mi * 32 + rr, idx = row * DM + col0 + lc;
;         const f32x4 xin = *(const f32x4*)(rin + idx);
;         v += xin;
;         *(f32x4*)(out + idx) = v;
;         *(u32x2*)(xb + row * LDX + col0 + lc) = pack4(v.x, v.y, v.z, v.w);
;         float ss = (v.x * v.x + v.y * v.y) + (v.z * v.z + v.w * v.w);
;         ss += __shfl_xor(ss, 1); ss += __shfl_xor(ss, 2); ss += __shfl_xor(ss, 4); ss += __shfl_xor(ss, 8);
;         if ((lane & 15) == 0) ssq[row * 16 + (col0 >> 6)] = ss;
;       }
.LBB0_554:
	s_or_b64 exec, exec, s[8:9]
	v_or_b32_e32 v34, v36, v112
	v_ashrrev_i32_e32 v35, 31, v34
	s_waitcnt lgkmcnt(0)
	v_lshlrev_b64 v[38:39], 12, v[34:35]
	v_lshl_add_u64 v[46:47], v[98:99], 0, v[38:39]
	flat_load_dwordx4 v[38:41], v[46:47]
	ds_read_b128 v[42:45], v108 offset:4352
	s_waitcnt vmcnt(0) lgkmcnt(0)
	v_add_f32_e64 v40, v44, v40
	v_add_f32_e64 v41, v45, v41
	v_add_f32_e64 v38, v42, v38
	v_add_f32_e64 v39, v43, v39
	v_mul_f32_e32 v42, v41, v41
	v_mul_f32_e32 v37, v39, v39
	v_fmac_f32_e32 v37, v38, v38
	v_fmac_f32_e32 v42, v40, v40
	v_add_f32_e32 v37, v37, v42
	ds_bpermute_b32 v42, v106, v37
	flat_store_dwordx4 v[46:47], v[38:41]
	v_cvt_pk_bf16_f32 v44, v38, v39
	v_cvt_pk_bf16_f32 v45, v40, v41
	s_waitcnt lgkmcnt(0)
	v_add_f32_e32 v37, v37, v42
	ds_bpermute_b32 v42, v105, v37
	s_waitcnt lgkmcnt(0)
	v_add_f32_e32 v37, v37, v42
	ds_bpermute_b32 v48, v104, v37
	v_mov_b64_e32 v[42:43], s[2:3]
	v_mad_i64_i32 v[40:41], s[8:9], v34, s74, v[42:43]
	v_lshl_add_u64 v[40:41], v[130:131], 1, v[40:41]
	s_waitcnt lgkmcnt(0)
	v_add_f32_e32 v37, v37, v48
	ds_bpermute_b32 v38, v107, v37
	v_lshl_add_u64 v[40:41], v[40:41], 0, v[32:33]
	flat_store_dwordx2 v[40:41], v[44:45]
	s_and_saveexec_b64 s[8:9], vcc
	s_cbranch_execz .LBB0_556
	v_lshlrev_b64 v[34:35], 6, v[34:35]
	v_lshl_add_u64 v[34:35], s[4:5], 0, v[34:35]
	v_lshl_add_u64 v[34:35], v[100:101], 2, v[34:35]
	s_waitcnt lgkmcnt(0)
	v_add_f32_e32 v37, v37, v38
	flat_store_dword v[34:35], v37
.LBB0_556:
	s_or_b64 exec, exec, s[8:9]
	v_or_b32_e32 v34, v36, v113
	v_ashrrev_i32_e32 v35, 31, v34
	s_waitcnt lgkmcnt(0)
	v_lshlrev_b64 v[38:39], 12, v[34:35]
	v_lshl_add_u64 v[46:47], v[98:99], 0, v[38:39]
	flat_load_dwordx4 v[38:41], v[46:47]
	ds_read_b128 v[42:45], v108 offset:5440
	s_waitcnt vmcnt(0) lgkmcnt(0)
	v_add_f32_e64 v40, v44, v40
	v_add_f32_e64 v41, v45, v41
	v_add_f32_e64 v38, v42, v38
	v_add_f32_e64 v39, v43, v39
	v_mul_f32_e32 v42, v41, v41
	v_mul_f32_e32 v37, v39, v39
	v_fmac_f32_e32 v37, v38, v38
	v_fmac_f32_e32 v42, v40, v40
	v_add_f32_e32 v37, v37, v42
	ds_bpermute_b32 v42, v106, v37
	flat_store_dwordx4 v[46:47], v[38:41]
	v_cvt_pk_bf16_f32 v44, v38, v39
	v_cvt_pk_bf16_f32 v45, v40, v41
	s_waitcnt lgkmcnt(0)
	v_add_f32_e32 v37, v37, v42
	ds_bpermute_b32 v42, v105, v37
	s_waitcnt lgkmcnt(0)
	v_add_f32_e32 v37, v37, v42
	ds_bpermute_b32 v48, v104, v37
	v_mov_b64_e32 v[42:43], s[2:3]
	v_mad_i64_i32 v[40:41], s[8:9], v34, s74, v[42:43]
	v_lshl_add_u64 v[40:41], v[130:131], 1, v[40:41]
	s_waitcnt lgkmcnt(0)
	v_add_f32_e32 v37, v37, v48
	ds_bpermute_b32 v38, v107, v37
	v_lshl_add_u64 v[40:41], v[40:41], 0, v[32:33]
	flat_store_dwordx2 v[40:41], v[44:45]
	s_and_saveexec_b64 s[8:9], vcc
	s_cbranch_execz .LBB0_558
	v_lshlrev_b64 v[34:35], 6, v[34:35]
	v_lshl_add_u64 v[34:35], s[4:5], 0, v[34:35]
	v_lshl_add_u64 v[34:35], v[100:101], 2, v[34:35]
	s_waitcnt lgkmcnt(0)
	v_add_f32_e32 v37, v37, v38
	flat_store_dword v[34:35], v37
.LBB0_558:
	s_or_b64 exec, exec, s[8:9]
	v_or_b32_e32 v34, v36, v114
	v_ashrrev_i32_e32 v35, 31, v34
	s_waitcnt lgkmcnt(0)
	v_lshlrev_b64 v[38:39], 12, v[34:35]
	v_lshl_add_u64 v[46:47], v[98:99], 0, v[38:39]
	flat_load_dwordx4 v[38:41], v[46:47]
	ds_read_b128 v[42:45], v108 offset:6528
	s_waitcnt vmcnt(0) lgkmcnt(0)
	v_add_f32_e64 v40, v44, v40
	v_add_f32_e64 v41, v45, v41
	v_add_f32_e64 v38, v42, v38
	v_add_f32_e64 v39, v43, v39
	v_mul_f32_e32 v42, v41, v41
	v_mul_f32_e32 v37, v39, v39
	v_fmac_f32_e32 v37, v38, v38
	v_fmac_f32_e32 v42, v40, v40
	v_add_f32_e32 v37, v37, v42
	ds_bpermute_b32 v42, v106, v37
	flat_store_dwordx4 v[46:47], v[38:41]
	v_cvt_pk_bf16_f32 v44, v38, v39
	v_cvt_pk_bf16_f32 v45, v40, v41
	s_waitcnt lgkmcnt(0)
	v_add_f32_e32 v37, v37, v42
	ds_bpermute_b32 v42, v105, v37
	s_waitcnt lgkmcnt(0)
	v_add_f32_e32 v37, v37, v42
	ds_bpermute_b32 v48, v104, v37
	v_mov_b64_e32 v[42:43], s[2:3]
	v_mad_i64_i32 v[40:41], s[8:9], v34, s74, v[42:43]
	v_lshl_add_u64 v[40:41], v[130:131], 1, v[40:41]
	s_waitcnt lgkmcnt(0)
	v_add_f32_e32 v37, v37, v48
	ds_bpermute_b32 v38, v107, v37
	v_lshl_add_u64 v[40:41], v[40:41], 0, v[32:33]
	flat_store_dwordx2 v[40:41], v[44:45]
	s_and_saveexec_b64 s[8:9], vcc
	s_cbranch_execz .LBB0_560
	v_lshlrev_b64 v[34:35], 6, v[34:35]
	v_lshl_add_u64 v[34:35], s[4:5], 0, v[34:35]
	v_lshl_add_u64 v[34:35], v[100:101], 2, v[34:35]
	s_waitcnt lgkmcnt(0)
	v_add_f32_e32 v37, v37, v38
	flat_store_dword v[34:35], v37
.LBB0_560:
	s_or_b64 exec, exec, s[8:9]
	v_or_b32_e32 v34, v36, v115
	v_ashrrev_i32_e32 v35, 31, v34
	v_lshlrev_b64 v[36:37], 12, v[34:35]
	v_lshl_add_u64 v[44:45], v[98:99], 0, v[36:37]
	s_waitcnt lgkmcnt(0)
	flat_load_dwordx4 v[36:39], v[44:45]
	ds_read_b128 v[40:43], v108 offset:7616
	s_waitcnt vmcnt(0) lgkmcnt(0)
	v_add_f32_e64 v38, v42, v38
	v_add_f32_e64 v39, v43, v39
	v_add_f32_e64 v36, v40, v36
	v_add_f32_e64 v37, v41, v37
	v_mul_f32_e32 v41, v39, v39
	v_mul_f32_e32 v40, v37, v37
	v_fmac_f32_e32 v40, v36, v36
	v_fmac_f32_e32 v41, v38, v38
	v_add_f32_e32 v40, v40, v41
	ds_bpermute_b32 v41, v106, v40
	flat_store_dwordx4 v[44:45], v[36:39]
	v_cvt_pk_bf16_f32 v42, v36, v37
	v_cvt_pk_bf16_f32 v43, v38, v39
	s_waitcnt lgkmcnt(0)
	v_add_f32_e32 v40, v40, v41
	ds_bpermute_b32 v41, v105, v40
	s_waitcnt lgkmcnt(0)
	v_add_f32_e32 v46, v40, v41
	ds_bpermute_b32 v47, v104, v46
	v_mov_b64_e32 v[40:41], s[2:3]
	v_mad_i64_i32 v[38:39], s[8:9], v34, s74, v[40:41]
	v_lshl_add_u64 v[38:39], v[130:131], 1, v[38:39]
	s_waitcnt lgkmcnt(0)
	v_add_f32_e32 v36, v46, v47
	ds_bpermute_b32 v37, v107, v36
	v_lshl_add_u64 v[38:39], v[38:39], 0, v[32:33]
	flat_store_dwordx2 v[38:39], v[42:43]
	s_and_saveexec_b64 s[8:9], vcc
	s_cbranch_execz .LBB0_562
	v_lshlrev_b64 v[34:35], 6, v[34:35]
	v_lshl_add_u64 v[34:35], s[4:5], 0, v[34:35]
	v_lshl_add_u64 v[34:35], v[100:101], 2, v[34:35]
	s_waitcnt lgkmcnt(0)
	v_add_f32_e32 v36, v36, v37
	flat_store_dword v[34:35], v36
; DI u32x2 pack4(float a, float b, float c, float d) { u32x2 w; w.x = pack2(a, b); w.y = pack2(c, d); return w; }
;   DI void operator()(const f32x16 (&acc)[4][2], bool vt, int row0, int col0, int r, int h, const float* sR, float* stage) const {
;     ...
;     for (int mi = 0; mi < 4; ++mi) {
; #pragma unroll
;       for (int ni = 0; ni < 2; ++ni)
; #pragma unroll
;         for (int g = 0; g < 4; ++g)
;           *(f32x4*)(stage + r * 68 + ni * 32 + 8 * g + 4 * h) = (f32x4){acc[mi][ni][4 * g], acc[mi][ni][4 * g + 1], acc[mi][ni][4 * g + 2], acc[mi][ni][4 * g + 3]};
; #pragma unroll
;       for (int j = 0; j < 8; ++j) {
;         const int rr = j * 4 + lr;
;         f32x4 v = *(const f32x4*)(stage + rr * 68 + lc);
;         const size_t row = row0 + mi * 32 + rr, idx = row * DM + col0 + lc;
;         const f32x4 xin = *(const f32x4*)(rin + idx);
;         v += xin;
;         *(f32x4*)(out + idx) = v;
;         *(u32x2*)(xb + row * LDX + col0 + lc) = pack4(v.x, v.y, v.z, v.w);
;         float ss = (v.x * v.x + v.y * v.y) + (v.z * v.z + v.w * v.w);
;         ss += __shfl_xor(ss, 1); ss += __shfl_xor(ss, 2); ss += __shfl_xor(ss, 4); ss += __shfl_xor(ss, 8);
;         if ((lane & 15) == 0) ssq[row * 16 + (col0 >> 6)] = ss;
;       }
.LBB0_562:
	s_or_b64 exec, exec, s[8:9]
	ds_write_b128 v133, v[16:19]
	ds_write_b128 v133, v[20:23] offset:32
	ds_write_b128 v133, v[24:27] offset:64
	ds_write_b128 v133, v[28:31] offset:96
	ds_write_b128 v133, v[0:3] offset:128
	ds_write_b128 v133, v[4:7] offset:160
	ds_write_b128 v133, v[8:11] offset:192
	ds_write_b128 v133, v[12:15] offset:224
	v_or_b32_e32 v2, 0x60, v132
	v_or_b32_e32 v0, v2, v142
	v_ashrrev_i32_e32 v1, 31, v0
	v_lshlrev_b64 v[4:5], 12, v[0:1]
	v_lshl_add_u64 v[12:13], v[98:99], 0, v[4:5]
	flat_load_dwordx4 v[4:7], v[12:13]
	ds_read_b128 v[8:11], v108
	s_waitcnt vmcnt(0) lgkmcnt(0)
	v_add_f32_e64 v6, v10, v6
	v_add_f32_e64 v7, v11, v7
	v_add_f32_e64 v4, v8, v4
	v_add_f32_e64 v5, v9, v5
	v_mul_f32_e32 v8, v7, v7
	v_mul_f32_e32 v3, v5, v5
	v_fmac_f32_e32 v3, v4, v4
	v_fmac_f32_e32 v8, v6, v6
	v_add_f32_e32 v3, v3, v8
	ds_bpermute_b32 v8, v106, v3
	flat_store_dwordx4 v[12:13], v[4:7]
	v_cvt_pk_bf16_f32 v10, v4, v5
	v_cvt_pk_bf16_f32 v11, v6, v7
	s_waitcnt lgkmcnt(0)
	v_add_f32_e32 v3, v3, v8
	ds_bpermute_b32 v8, v105, v3
	s_waitcnt lgkmcnt(0)
	v_add_f32_e32 v3, v3, v8
	ds_bpermute_b32 v14, v104, v3
	v_mov_b64_e32 v[8:9], s[2:3]
	v_mad_i64_i32 v[6:7], s[8:9], v0, s74, v[8:9]
	v_lshl_add_u64 v[6:7], v[130:131], 1, v[6:7]
	s_waitcnt lgkmcnt(0)
	v_add_f32_e32 v3, v3, v14
	ds_bpermute_b32 v4, v107, v3
	v_lshl_add_u64 v[6:7], v[6:7], 0, v[32:33]
	flat_store_dwordx2 v[6:7], v[10:11]
	s_and_saveexec_b64 s[8:9], vcc
	s_cbranch_execz .LBB0_564
	v_lshlrev_b64 v[0:1], 6, v[0:1]
	v_lshl_add_u64 v[0:1], s[4:5], 0, v[0:1]
	v_lshl_add_u64 v[0:1], v[100:101], 2, v[0:1]
	s_waitcnt lgkmcnt(0)
	v_add_f32_e32 v3, v3, v4
	flat_store_dword v[0:1], v3
.LBB0_564:
	s_or_b64 exec, exec, s[8:9]
	v_or_b32_e32 v0, v2, v109
	v_ashrrev_i32_e32 v1, 31, v0
	s_waitcnt lgkmcnt(0)
	v_lshlrev_b64 v[4:5], 12, v[0:1]
	v_lshl_add_u64 v[12:13], v[98:99], 0, v[4:5]
	flat_load_dwordx4 v[4:7], v[12:13]
	ds_read_b128 v[8:11], v108 offset:1088
	s_waitcnt vmcnt(0) lgkmcnt(0)
	v_add_f32_e64 v6, v10, v6
	v_add_f32_e64 v7, v11, v7
	v_add_f32_e64 v4, v8, v4
	v_add_f32_e64 v5, v9, v5
	v_mul_f32_e32 v8, v7, v7
	v_mul_f32_e32 v3, v5, v5
	v_fmac_f32_e32 v3, v4, v4
	v_fmac_f32_e32 v8, v6, v6
	v_add_f32_e32 v3, v3, v8
	ds_bpermute_b32 v8, v106, v3
	flat_store_dwordx4 v[12:13], v[4:7]
	v_cvt_pk_bf16_f32 v10, v4, v5
	v_cvt_pk_bf16_f32 v11, v6, v7
	s_waitcnt lgkmcnt(0)
	v_add_f32_e32 v3, v3, v8
	ds_bpermute_b32 v8, v105, v3
	s_waitcnt lgkmcnt(0)
	v_add_f32_e32 v3, v3, v8
	ds_bpermute_b32 v14, v104, v3
	v_mov_b64_e32 v[8:9], s[2:3]
	v_mad_i64_i32 v[6:7], s[8:9], v0, s74, v[8:9]
	v_lshl_add_u64 v[6:7], v[130:131], 1, v[6:7]
	s_waitcnt lgkmcnt(0)
	v_add_f32_e32 v3, v3, v14
	ds_bpermute_b32 v4, v107, v3
	v_lshl_add_u64 v[6:7], v[6:7], 0, v[32:33]
	flat_store_dwordx2 v[6:7], v[10:11]
	s_and_saveexec_b64 s[8:9], vcc
	s_cbranch_execz .LBB0_566
	v_lshlrev_b64 v[0:1], 6, v[0:1]
	v_lshl_add_u64 v[0:1], s[4:5], 0, v[0:1]
	v_lshl_add_u64 v[0:1], v[100:101], 2, v[0:1]
	s_waitcnt lgkmcnt(0)
	v_add_f32_e32 v3, v3, v4
	flat_store_dword v[0:1], v3
.LBB0_566:
	s_or_b64 exec, exec, s[8:9]
	v_or_b32_e32 v0, v2, v110
	v_ashrrev_i32_e32 v1, 31, v0
	s_waitcnt lgkmcnt(0)
	v_lshlrev_b64 v[4:5], 12, v[0:1]
	v_lshl_add_u64 v[12:13], v[98:99], 0, v[4:5]
	flat_load_dwordx4 v[4:7], v[12:13]
	ds_read_b128 v[8:11], v108 offset:2176
	s_waitcnt vmcnt(0) lgkmcnt(0)
	v_add_f32_e64 v6, v10, v6
	v_add_f32_e64 v7, v11, v7
	v_add_f32_e64 v4, v8, v4
	v_add_f32_e64 v5, v9, v5
	v_mul_f32_e32 v8, v7, v7
	v_mul_f32_e32 v3, v5, v5
	v_fmac_f32_e32 v3, v4, v4
	v_fmac_f32_e32 v8, v6, v6
	v_add_f32_e32 v3, v3, v8
	ds_bpermute_b32 v8, v106, v3
	flat_store_dwordx4 v[12:13], v[4:7]
	v_cvt_pk_bf16_f32 v10, v4, v5
	v_cvt_pk_bf16_f32 v11, v6, v7
	s_waitcnt lgkmcnt(0)
	v_add_f32_e32 v3, v3, v8
	ds_bpermute_b32 v8, v105, v3
	s_waitcnt lgkmcnt(0)
	v_add_f32_e32 v3, v3, v8
	ds_bpermute_b32 v14, v104, v3
	v_mov_b64_e32 v[8:9], s[2:3]
	v_mad_i64_i32 v[6:7], s[8:9], v0, s74, v[8:9]
	v_lshl_add_u64 v[6:7], v[130:131], 1, v[6:7]
	s_waitcnt lgkmcnt(0)
	v_add_f32_e32 v3, v3, v14
	ds_bpermute_b32 v4, v107, v3
	v_lshl_add_u64 v[6:7], v[6:7], 0, v[32:33]
	flat_store_dwordx2 v[6:7], v[10:11]
	s_and_saveexec_b64 s[8:9], vcc
	s_cbranch_execz .LBB0_568
	v_lshlrev_b64 v[0:1], 6, v[0:1]
	v_lshl_add_u64 v[0:1], s[4:5], 0, v[0:1]
	v_lshl_add_u64 v[0:1], v[100:101], 2, v[0:1]
	s_waitcnt lgkmcnt(0)
	v_add_f32_e32 v3, v3, v4
	flat_store_dword v[0:1], v3
.LBB0_568:
	s_or_b64 exec, exec, s[8:9]
	v_or_b32_e32 v0, v2, v111
	v_ashrrev_i32_e32 v1, 31, v0
	s_waitcnt lgkmcnt(0)
	v_lshlrev_b64 v[4:5], 12, v[0:1]
	v_lshl_add_u64 v[12:13], v[98:99], 0, v[4:5]
	flat_load_dwordx4 v[4:7], v[12:13]
	ds_read_b128 v[8:11], v108 offset:3264
	s_waitcnt vmcnt(0) lgkmcnt(0)
	v_add_f32_e64 v6, v10, v6
	v_add_f32_e64 v7, v11, v7
	v_add_f32_e64 v4, v8, v4
	v_add_f32_e64 v5, v9, v5
	v_mul_f32_e32 v8, v7, v7
	v_mul_f32_e32 v3, v5, v5
	v_fmac_f32_e32 v3, v4, v4
	v_fmac_f32_e32 v8, v6, v6
	v_add_f32_e32 v3, v3, v8
	ds_bpermute_b32 v8, v106, v3
	flat_store_dwordx4 v[12:13], v[4:7]
	v_cvt_pk_bf16_f32 v10, v4, v5
	v_cvt_pk_bf16_f32 v11, v6, v7
	s_waitcnt lgkmcnt(0)
	v_add_f32_e32 v3, v3, v8
	ds_bpermute_b32 v8, v105, v3
	s_waitcnt lgkmcnt(0)
	v_add_f32_e32 v3, v3, v8
	ds_bpermute_b32 v14, v104, v3
	v_mov_b64_e32 v[8:9], s[2:3]
	v_mad_i64_i32 v[6:7], s[8:9], v0, s74, v[8:9]
	v_lshl_add_u64 v[6:7], v[130:131], 1, v[6:7]
	s_waitcnt lgkmcnt(0)
	v_add_f32_e32 v3, v3, v14
	ds_bpermute_b32 v4, v107, v3
	v_lshl_add_u64 v[6:7], v[6:7], 0, v[32:33]
	flat_store_dwordx2 v[6:7], v[10:11]
	s_and_saveexec_b64 s[8:9], vcc
	s_cbranch_execz .LBB0_570
	v_lshlrev_b64 v[0:1], 6, v[0:1]
	v_lshl_add_u64 v[0:1], s[4:5], 0, v[0:1]
	v_lshl_add_u64 v[0:1], v[100:101], 2, v[0:1]
	s_waitcnt lgkmcnt(0)
	v_add_f32_e32 v3, v3, v4
	flat_store_dword v[0:1], v3
; DI u32x2 pack4(float a, float b, float c, float d) { u32x2 w; w.x = pack2(a, b); w.y = pack2(c, d); return w; }
;   DI void operator()(const f32x16 (&acc)[4][2], bool vt, int row0, int col0, int r, int h, const float* sR, float* stage) const {
;     ...
; #pragma unroll
;       for (int j = 0; j < 8; ++j) {
;         const int rr = j * 4 + lr;
;         f32x4 v = *(const f32x4*)(stage + rr * 68 + lc);
;         const size_t row = row0 + mi * 32 + rr, idx = row * DM + col0 + lc;
;         const f32x4 xin = *(const f32x4*)(rin + idx);
;         v += xin;
;         *(f32x4*)(out + idx) = v;
;         *(u32x2*)(xb + row * LDX + col0 + lc) = pack4(v.x, v.y, v.z, v.w);
;         float ss = (v.x * v.x + v.y * v.y) + (v.z * v.z + v.w * v.w);
;         ss += __shfl_xor(ss, 1); ss += __shfl_xor(ss, 2); ss += __shfl_xor(ss, 4); ss += __shfl_xor(ss, 8);
;         if ((lane & 15) == 0) ssq[row * 16 + (col0 >> 6)] = ss;
;       }
.LBB0_570:
	s_or_b64 exec, exec, s[8:9]
	v_or_b32_e32 v0, v2, v112
	v_ashrrev_i32_e32 v1, 31, v0
	s_waitcnt lgkmcnt(0)
	v_lshlrev_b64 v[4:5], 12, v[0:1]
	v_lshl_add_u64 v[12:13], v[98:99], 0, v[4:5]
	flat_load_dwordx4 v[4:7], v[12:13]
	ds_read_b128 v[8:11], v108 offset:4352
	s_waitcnt vmcnt(0) lgkmcnt(0)
	v_add_f32_e64 v6, v10, v6
	v_add_f32_e64 v7, v11, v7
	v_add_f32_e64 v4, v8, v4
	v_add_f32_e64 v5, v9, v5
	v_mul_f32_e32 v8, v7, v7
	v_mul_f32_e32 v3, v5, v5
	v_fmac_f32_e32 v3, v4, v4
	v_fmac_f32_e32 v8, v6, v6
	v_add_f32_e32 v3, v3, v8
	ds_bpermute_b32 v8, v106, v3
	flat_store_dwordx4 v[12:13], v[4:7]
	v_cvt_pk_bf16_f32 v10, v4, v5
	v_cvt_pk_bf16_f32 v11, v6, v7
	s_waitcnt lgkmcnt(0)
	v_add_f32_e32 v3, v3, v8
	ds_bpermute_b32 v8, v105, v3
	s_waitcnt lgkmcnt(0)
	v_add_f32_e32 v3, v3, v8
	ds_bpermute_b32 v14, v104, v3
	v_mov_b64_e32 v[8:9], s[2:3]
	v_mad_i64_i32 v[6:7], s[8:9], v0, s74, v[8:9]
	v_lshl_add_u64 v[6:7], v[130:131], 1, v[6:7]
	s_waitcnt lgkmcnt(0)
	v_add_f32_e32 v3, v3, v14
	ds_bpermute_b32 v4, v107, v3
	v_lshl_add_u64 v[6:7], v[6:7], 0, v[32:33]
	flat_store_dwordx2 v[6:7], v[10:11]
	s_and_saveexec_b64 s[8:9], vcc
	s_cbranch_execz .LBB0_572
	v_lshlrev_b64 v[0:1], 6, v[0:1]
	v_lshl_add_u64 v[0:1], s[4:5], 0, v[0:1]
	v_lshl_add_u64 v[0:1], v[100:101], 2, v[0:1]
	s_waitcnt lgkmcnt(0)
	v_add_f32_e32 v3, v3, v4
	flat_store_dword v[0:1], v3
.LBB0_572:
	s_or_b64 exec, exec, s[8:9]
	v_or_b32_e32 v0, v2, v113
	v_ashrrev_i32_e32 v1, 31, v0
	s_waitcnt lgkmcnt(0)
	v_lshlrev_b64 v[4:5], 12, v[0:1]
	v_lshl_add_u64 v[12:13], v[98:99], 0, v[4:5]
	flat_load_dwordx4 v[4:7], v[12:13]
	ds_read_b128 v[8:11], v108 offset:5440
	s_waitcnt vmcnt(0) lgkmcnt(0)
	v_add_f32_e64 v6, v10, v6
	v_add_f32_e64 v7, v11, v7
	v_add_f32_e64 v4, v8, v4
	v_add_f32_e64 v5, v9, v5
	v_mul_f32_e32 v8, v7, v7
	v_mul_f32_e32 v3, v5, v5
	v_fmac_f32_e32 v3, v4, v4
	v_fmac_f32_e32 v8, v6, v6
	v_add_f32_e32 v3, v3, v8
	ds_bpermute_b32 v8, v106, v3
	flat_store_dwordx4 v[12:13], v[4:7]
	v_cvt_pk_bf16_f32 v10, v4, v5
	v_cvt_pk_bf16_f32 v11, v6, v7
	s_waitcnt lgkmcnt(0)
	v_add_f32_e32 v3, v3, v8
	ds_bpermute_b32 v8, v105, v3
	s_waitcnt lgkmcnt(0)
	v_add_f32_e32 v3, v3, v8
	ds_bpermute_b32 v14, v104, v3
	v_mov_b64_e32 v[8:9], s[2:3]
	v_mad_i64_i32 v[6:7], s[8:9], v0, s74, v[8:9]
	v_lshl_add_u64 v[6:7], v[130:131], 1, v[6:7]
	s_waitcnt lgkmcnt(0)
	v_add_f32_e32 v3, v3, v14
	ds_bpermute_b32 v4, v107, v3
	v_lshl_add_u64 v[6:7], v[6:7], 0, v[32:33]
	flat_store_dwordx2 v[6:7], v[10:11]
	s_and_saveexec_b64 s[8:9], vcc
	s_cbranch_execz .LBB0_574
	v_lshlrev_b64 v[0:1], 6, v[0:1]
	v_lshl_add_u64 v[0:1], s[4:5], 0, v[0:1]
	v_lshl_add_u64 v[0:1], v[100:101], 2, v[0:1]
	s_waitcnt lgkmcnt(0)
	v_add_f32_e32 v3, v3, v4
	flat_store_dword v[0:1], v3
.LBB0_574:
	s_or_b64 exec, exec, s[8:9]
	v_or_b32_e32 v0, v2, v114
	v_ashrrev_i32_e32 v1, 31, v0
	s_waitcnt lgkmcnt(0)
	v_lshlrev_b64 v[4:5], 12, v[0:1]
	v_lshl_add_u64 v[12:13], v[98:99], 0, v[4:5]
	flat_load_dwordx4 v[4:7], v[12:13]
	ds_read_b128 v[8:11], v108 offset:6528
	s_waitcnt vmcnt(0) lgkmcnt(0)
	v_add_f32_e64 v6, v10, v6
	v_add_f32_e64 v7, v11, v7
	v_add_f32_e64 v4, v8, v4
	v_add_f32_e64 v5, v9, v5
	v_mul_f32_e32 v8, v7, v7
	v_mul_f32_e32 v3, v5, v5
	v_fmac_f32_e32 v3, v4, v4
	v_fmac_f32_e32 v8, v6, v6
	v_add_f32_e32 v3, v3, v8
	ds_bpermute_b32 v8, v106, v3
	flat_store_dwordx4 v[12:13], v[4:7]
	v_cvt_pk_bf16_f32 v10, v4, v5
	v_cvt_pk_bf16_f32 v11, v6, v7
	s_waitcnt lgkmcnt(0)
	v_add_f32_e32 v3, v3, v8
	ds_bpermute_b32 v8, v105, v3
	s_waitcnt lgkmcnt(0)
	v_add_f32_e32 v3, v3, v8
	ds_bpermute_b32 v14, v104, v3
	v_mov_b64_e32 v[8:9], s[2:3]
	v_mad_i64_i32 v[6:7], s[8:9], v0, s74, v[8:9]
	v_lshl_add_u64 v[6:7], v[130:131], 1, v[6:7]
	s_waitcnt lgkmcnt(0)
	v_add_f32_e32 v3, v3, v14
	ds_bpermute_b32 v4, v107, v3
	v_lshl_add_u64 v[6:7], v[6:7], 0, v[32:33]
	flat_store_dwordx2 v[6:7], v[10:11]
	s_and_saveexec_b64 s[8:9], vcc
	s_cbranch_execz .LBB0_576
	v_lshlrev_b64 v[0:1], 6, v[0:1]
	v_lshl_add_u64 v[0:1], s[4:5], 0, v[0:1]
	v_lshl_add_u64 v[0:1], v[100:101], 2, v[0:1]
	s_waitcnt lgkmcnt(0)
	v_add_f32_e32 v3, v3, v4
	flat_store_dword v[0:1], v3
.LBB0_576:
	s_or_b64 exec, exec, s[8:9]
	v_or_b32_e32 v0, v2, v115
	v_ashrrev_i32_e32 v1, 31, v0
	v_lshlrev_b64 v[2:3], 12, v[0:1]
	v_lshl_add_u64 v[10:11], v[98:99], 0, v[2:3]
	s_waitcnt lgkmcnt(0)
	flat_load_dwordx4 v[2:5], v[10:11]
	ds_read_b128 v[6:9], v108 offset:7616
	s_waitcnt vmcnt(0) lgkmcnt(0)
	v_add_f32_e64 v4, v8, v4
	v_add_f32_e64 v5, v9, v5
	v_add_f32_e64 v2, v6, v2
	v_add_f32_e64 v3, v7, v3
	v_mul_f32_e32 v7, v5, v5
	v_mul_f32_e32 v6, v3, v3
	v_fmac_f32_e32 v6, v2, v2
	v_fmac_f32_e32 v7, v4, v4
	v_add_f32_e32 v6, v6, v7
	ds_bpermute_b32 v7, v106, v6
	flat_store_dwordx4 v[10:11], v[2:5]
	v_cvt_pk_bf16_f32 v8, v2, v3
	v_cvt_pk_bf16_f32 v9, v4, v5
	s_waitcnt lgkmcnt(0)
	v_add_f32_e32 v6, v6, v7
	ds_bpermute_b32 v7, v105, v6
	s_waitcnt lgkmcnt(0)
	v_add_f32_e32 v12, v6, v7
	ds_bpermute_b32 v13, v104, v12
	v_mov_b64_e32 v[6:7], s[2:3]
	v_mad_i64_i32 v[4:5], s[8:9], v0, s74, v[6:7]
	v_lshl_add_u64 v[4:5], v[130:131], 1, v[4:5]
	s_waitcnt lgkmcnt(0)
	v_add_f32_e32 v2, v12, v13
	ds_bpermute_b32 v3, v107, v2
	v_lshl_add_u64 v[4:5], v[4:5], 0, v[32:33]
	flat_store_dwordx2 v[4:5], v[8:9]
	s_and_saveexec_b64 s[8:9], vcc
	s_cbranch_execz .LBB0_511
	v_lshlrev_b64 v[0:1], 6, v[0:1]
	v_lshl_add_u64 v[0:1], s[4:5], 0, v[0:1]
	v_lshl_add_u64 v[0:1], v[100:101], 2, v[0:1]
	s_waitcnt lgkmcnt(0)
	v_add_f32_e32 v2, v2, v3
	flat_store_dword v[0:1], v2
	s_branch .LBB0_511

; #define MFMA(a, b, c) __builtin_amdgcn_mfma_f32_32x32x16_bf16((a), (b), (c), 0, 0, 0)
; DI u32x2 pack4(float a, float b, float c, float d) { u32x2 w; w.x = pack2(a, b); w.y = pack2(c, d); return w; }
; template <bool VT>
; DI void g_compute_asm(unsigned aA0, unsigned aA1, unsigned aB0, unsigned aB1, f32x16 (&acc)[4][2]) {
;     ...
;       else acc[mi][ni] = MFMA(b0[ni], a0[mi], acc[mi][ni]);
;     }
;   __builtin_amdgcn_sched_barrier(0);
;   asm volatile("s_waitcnt lgkmcnt(0)" : "+v"(b1[0]), "+v"(b1[1]), "+v"(a1[0]), "+v"(a1[1]), "+v"(a1[2]), "+v"(a1[3]));
; #pragma unroll
;   for (int mi = 0; mi < 4; ++mi)
; #pragma unroll
;     for (int ni = 0; ni < 2; ++ni) {
;       if (VT) acc[mi][ni] = MFMA(a1[mi], b1[ni], acc[mi][ni]);
;       else acc[mi][ni] = MFMA(b1[ni], a1[mi], acc[mi][ni]);
;     }
;   DI void operator()(const f32x16 (&acc)[4][2], bool vt, int row0, int col0, int r, int h, const float* sR, float* stage) const {
;     bf16_t* st = (bf16_t*)stage;
;     const int lane = h * 32 + r;
; #pragma unroll
;     for (int mi = 0; mi < 4; ++mi) {
;       const float rv = sR[mi * 32 + r];
; #pragma unroll
;       for (int g = 0; g < 4; ++g) {
;         float o[4];
; #pragma unroll
;         for (int q = 0; q < 4; ++q) {
;           const float gt = acc[mi][0][4 * g + q] * rv, up = acc[mi][1][4 * g + q] * rv;
;           o[q] = gt * __builtin_amdgcn_rcpf(1.f + __expf(-gt)) * up;
;         }
;         *(u32x2*)(st + r * 40 + 8 * g + 4 * h) = pack4(o[0], o[1], o[2], o[3]);
;       }
.LBB0_1251:
	s_mul_i32 s10, s14, 0x6000
	v_add_u32_e32 v138, s10, v159
	v_lshl_or_b32 v150, v156, 6, s27
	v_add_u32_e32 v32, s10, v157
	v_add_u32_e32 v151, s10, v158
	v_add_u32_e32 v168, s10, v160
	ds_read_b128 v[130:133], v138 offset:0
	ds_read_b128 v[134:137], v138 offset:2048
	ds_read_b128 v[138:141], v32 offset:0
	ds_read_b128 v[142:145], v32 offset:2048
	ds_read_b128 v[146:149], v32 offset:4096
	ds_read_b128 v[156:159], v32 offset:6144
	ds_read_b128 v[160:163], v168 offset:0
	ds_read_b128 v[164:167], v168 offset:2048
	ds_read_b128 v[168:171], v151 offset:0
	ds_read_b128 v[172:175], v151 offset:2048
	ds_read_b128 v[176:179], v151 offset:4096
	ds_read_b128 v[180:183], v151 offset:6144
	s_nop 0
	s_waitcnt lgkmcnt(6)
	s_nop 0
	v_mfma_f32_32x32x16_bf16 v[114:129], v[130:133], v[138:141], v[114:129]
	v_mfma_f32_32x32x16_bf16 v[98:113], v[134:137], v[138:141], v[98:113]
	v_mfma_f32_32x32x16_bf16 v[82:97], v[130:133], v[142:145], v[82:97]
	v_mfma_f32_32x32x16_bf16 v[66:81], v[134:137], v[142:145], v[66:81]
	v_mfma_f32_32x32x16_bf16 v[50:65], v[130:133], v[146:149], v[50:65]
	v_mfma_f32_32x32x16_bf16 v[34:49], v[134:137], v[146:149], v[34:49]
	v_mfma_f32_32x32x16_bf16 v[16:31], v[130:133], v[156:159], v[16:31]
	v_mfma_f32_32x32x16_bf16 v[0:15], v[134:137], v[156:159], v[0:15]
	v_mul_lo_u32 v32, v153, s75
	s_waitcnt lgkmcnt(0)
	v_add_u32_e32 v130, s10, v32
	v_mfma_f32_32x32x16_bf16 v[114:129], v[160:163], v[168:171], v[114:129]
	v_and_b32_e32 v32, 0xffffff80, v152
	v_or_b32_e32 v132, v32, v154
	v_lshl_add_u32 v137, v132, 2, v210
	s_waitcnt lgkmcnt(0)
	s_waitcnt vmcnt(0) lgkmcnt(0)
	s_barrier
	ds_read_b32 v132, v137
	v_add_u32_e32 v133, s25, v32
	v_mfma_f32_32x32x16_bf16 v[98:113], v[164:167], v[168:171], v[98:113]
	s_movk_i32 s10, 0x50
	v_mad_u32_u24 v32, v154, s10, v130
	s_waitcnt lgkmcnt(0)
	s_nop 0
	v_mul_f32_e64 v114, v114, v132
	v_mul_f32_e64 v115, v115, v132
	v_lshl_or_b32 v135, v155, 3, v32
	v_mul_f32_e32 v138, 0xbfb8aa3b, v114
	v_mul_f32_e32 v139, 0xbfb8aa3b, v115
	v_exp_f32_e32 v138, v138
	v_exp_f32_e32 v139, v139
	s_nop 0
	v_mul_f32_e64 v98, v98, v132
	v_mul_f32_e64 v99, v99, v132
	v_mul_f32_e64 v100, v100, v132
	v_mul_f32_e64 v101, v101, v132
	v_add_f32_e32 v138, 1.0, v138
	v_add_f32_e32 v139, 1.0, v139
	v_rcp_f32_e32 v138, v138
	v_rcp_f32_e32 v139, v139
	v_mul_f32_e64 v102, v102, v132
	v_mul_f32_e64 v103, v103, v132
	v_mul_f32_e64 v104, v104, v132
	v_mul_f32_e64 v105, v105, v132
	v_lshlrev_b32_e32 v32, 4, v154
	v_mul_f32_e64 v114, v114, v138
	v_mul_f32_e64 v115, v115, v139
	v_and_b32_e32 v32, 48, v32
	v_mul_f32_e64 v98, v98, v114
	v_mul_f32_e64 v99, v99, v115
	v_mul_f32_e64 v114, v116, v132
	v_mul_f32_e64 v115, v117, v132
	v_cvt_pk_bf16_f32 v98, v98, v99
	v_mul_f32_e32 v116, 0xbfb8aa3b, v114
	v_mul_f32_e32 v117, 0xbfb8aa3b, v115
	v_exp_f32_e32 v116, v116
	v_exp_f32_e32 v117, v117
	v_bfe_u32 v134, v152, 2, 4
	v_or_b32_e32 v136, v130, v32
	v_add_f32_e32 v116, 1.0, v116
	v_add_f32_e32 v117, 1.0, v117
	v_rcp_f32_e32 v116, v116
	v_rcp_f32_e32 v117, v117
	v_mad_u32_u24 v136, v134, s10, v136
	v_ashrrev_i32_e32 v130, 1, v150
	v_ashrrev_i32_e32 v131, 31, v130
	v_mul_f32_e64 v114, v114, v116
	v_mul_f32_e64 v115, v115, v117
	s_movk_i32 s12, 0x1680
	v_mul_f32_e64 v100, v100, v114
	v_mul_f32_e64 v101, v101, v115
	v_mfma_f32_32x32x16_bf16 v[82:97], v[160:163], v[172:175], v[82:97]
	v_cvt_pk_bf16_f32 v99, v100, v101
	ds_write_b64 v135, v[98:99]
	v_mul_f32_e64 v98, v118, v132
	v_mul_f32_e64 v99, v119, v132
	s_cmp_lg_u32 s14, 2
	v_mul_f32_e32 v100, 0xbfb8aa3b, v98
	v_mul_f32_e32 v101, 0xbfb8aa3b, v99
	v_exp_f32_e32 v100, v100
	v_exp_f32_e32 v101, v101
	v_mfma_f32_32x32x16_bf16 v[66:81], v[164:167], v[172:175], v[66:81]
	s_cselect_b32 s26, s15, 0
	v_add_f32_e32 v100, 1.0, v100
	v_add_f32_e32 v101, 1.0, v101
	v_rcp_f32_e32 v100, v100
	v_rcp_f32_e32 v101, v101
	s_add_i32 s23, s23, s20
	s_andn2_b64 vcc, exec, s[6:7]
	v_mfma_f32_32x32x16_bf16 v[50:65], v[160:163], v[176:179], v[50:65]
	v_mul_f32_e64 v98, v98, v100
	v_mul_f32_e64 v99, v99, v101
	v_mul_f32_e64 v100, v120, v132
	v_mul_f32_e64 v101, v121, v132
	v_mul_f32_e64 v98, v102, v98
	v_mul_f32_e64 v99, v103, v99
	v_mul_f32_e32 v102, 0xbfb8aa3b, v100
	v_mul_f32_e32 v103, 0xbfb8aa3b, v101
	v_exp_f32_e32 v102, v102
	v_exp_f32_e32 v103, v103
	v_cvt_pk_bf16_f32 v98, v98, v99
	v_mfma_f32_32x32x16_bf16 v[34:49], v[164:167], v[176:179], v[34:49]
	v_add_f32_e32 v102, 1.0, v102
	v_add_f32_e32 v103, 1.0, v103
	v_rcp_f32_e32 v102, v102
	v_rcp_f32_e32 v103, v103
	s_mov_b32 s13, s24
	v_mul_f32_e64 v100, v100, v102
	v_mul_f32_e64 v101, v101, v103
	s_nop 0
	v_mul_f32_e64 v100, v104, v100
	v_mul_f32_e64 v101, v105, v101
	v_mul_f32_e64 v102, v106, v132
	v_mul_f32_e64 v103, v107, v132
	v_cvt_pk_bf16_f32 v99, v100, v101
	ds_write_b64 v135, v[98:99] offset:16
	v_mul_f32_e64 v98, v122, v132
	v_mul_f32_e64 v99, v123, v132
	v_mul_f32_e64 v104, v108, v132
	v_mul_f32_e64 v105, v109, v132
	v_mul_f32_e32 v100, 0xbfb8aa3b, v98
	v_mul_f32_e32 v101, 0xbfb8aa3b, v99
	v_exp_f32_e32 v100, v100
	v_exp_f32_e32 v101, v101
	v_mfma_f32_32x32x16_bf16 v[16:31], v[160:163], v[180:183], v[16:31]
	v_add_f32_e32 v100, 1.0, v100
	v_add_f32_e32 v101, 1.0, v101
	v_rcp_f32_e32 v100, v100
	v_rcp_f32_e32 v101, v101
	s_nop 0
	v_mul_f32_e64 v98, v98, v100
	v_mul_f32_e64 v99, v99, v101
	v_mul_f32_e64 v100, v124, v132
	v_mul_f32_e64 v101, v125, v132
	v_mul_f32_e64 v98, v102, v98
	v_mul_f32_e64 v99, v103, v99
	v_mul_f32_e32 v102, 0xbfb8aa3b, v100
	v_mul_f32_e32 v103, 0xbfb8aa3b, v101
	v_exp_f32_e32 v102, v102
	v_exp_f32_e32 v103, v103
	v_cvt_pk_bf16_f32 v98, v98, v99
	v_mfma_f32_32x32x16_bf16 v[0:15], v[164:167], v[180:183], v[0:15]
	v_add_f32_e32 v102, 1.0, v102
; DI u32x2 pack4(float a, float b, float c, float d) { u32x2 w; w.x = pack2(a, b); w.y = pack2(c, d); return w; }
;   DI void operator()(const f32x16 (&acc)[4][2], bool vt, int row0, int col0, int r, int h, const float* sR, float* stage) const {
;     ...
;       const float rv = sR[mi * 32 + r];
; #pragma unroll
;       for (int g = 0; g < 4; ++g) {
;         float o[4];
; #pragma unroll
;         for (int q = 0; q < 4; ++q) {
;           const float gt = acc[mi][0][4 * g + q] * rv, up = acc[mi][1][4 * g + q] * rv;
;           o[q] = gt * __builtin_amdgcn_rcpf(1.f + __expf(-gt)) * up;
;         }
;         *(u32x2*)(st + r * 40 + 8 * g + 4 * h) = pack4(o[0], o[1], o[2], o[3]);
;       }
; #pragma unroll
;       for (int j = 0; j < 2; ++j) {
;         const int rr = j * 16 + (lane >> 2), cc = (lane & 3) * 8;
;         const u32x4 v = *(const u32x4*)(st + rr * 40 + cc);
;         *(u32x4*)(act + (size_t)(row0 + mi * 32 + rr) * LDF + (col0 >> 1) + cc) = v;
;       }
	v_add_f32_e32 v103, 1.0, v103
	v_rcp_f32_e32 v102, v102
	v_rcp_f32_e32 v103, v103
	s_nop 0
	v_mul_f32_e64 v100, v100, v102
	v_mul_f32_e64 v101, v101, v103
	s_nop 0
	v_mul_f32_e64 v100, v104, v100
	v_mul_f32_e64 v101, v105, v101
	v_mul_f32_e64 v102, v110, v132
	v_mul_f32_e64 v103, v111, v132
	v_cvt_pk_bf16_f32 v99, v100, v101
	ds_write_b64 v135, v[98:99] offset:32
	v_mul_f32_e64 v98, v126, v132
	v_mul_f32_e64 v99, v127, v132
	v_mul_f32_e64 v104, v112, v132
	v_mul_f32_e64 v105, v113, v132
	v_mul_f32_e32 v100, 0xbfb8aa3b, v98
	v_mul_f32_e32 v101, 0xbfb8aa3b, v99
	v_exp_f32_e32 v100, v100
	v_exp_f32_e32 v101, v101
	v_add_f32_e32 v100, 1.0, v100
	v_add_f32_e32 v101, 1.0, v101
	v_rcp_f32_e32 v100, v100
	v_rcp_f32_e32 v101, v101
	s_nop 0
	v_mul_f32_e64 v98, v98, v100
	v_mul_f32_e64 v99, v99, v101
	v_mul_f32_e64 v100, v128, v132
	v_mul_f32_e64 v101, v129, v132
	v_mul_f32_e64 v98, v102, v98
	v_mul_f32_e64 v99, v103, v99
	v_mul_f32_e32 v102, 0xbfb8aa3b, v100
	v_mul_f32_e32 v103, 0xbfb8aa3b, v101
	v_exp_f32_e32 v102, v102
	v_exp_f32_e32 v103, v103
	v_cvt_pk_bf16_f32 v98, v98, v99
	v_add_f32_e32 v102, 1.0, v102
	v_add_f32_e32 v103, 1.0, v103
	v_rcp_f32_e32 v102, v102
	v_rcp_f32_e32 v103, v103
	s_nop 0
	v_mul_f32_e64 v100, v100, v102
	v_mul_f32_e64 v101, v101, v103
	s_nop 0
	v_mul_f32_e64 v100, v104, v100
	v_mul_f32_e64 v101, v105, v101
	s_nop 0
	v_cvt_pk_bf16_f32 v99, v100, v101
	ds_write_b64 v135, v[98:99] offset:48
	ds_read_b128 v[102:105], v136
	v_or_b32_e32 v100, v133, v134
	v_mov_b64_e32 v[98:99], s[2:3]
	v_mad_i64_i32 v[106:107], s[10:11], v100, s12, v[98:99]
	v_lshlrev_b64 v[100:101], 1, v[130:131]
	v_lshl_add_u64 v[106:107], v[106:107], 0, v[100:101]
	v_lshl_add_u64 v[106:107], v[106:107], 0, v[32:33]
	s_waitcnt lgkmcnt(0)
	flat_store_dwordx4 v[106:107], v[102:105]
	ds_read_b128 v[104:107], v136 offset:1280
	s_nop 0
	v_or_b32_e32 v103, 16, v134
	v_or_b32_e32 v102, v103, v133
	v_mad_i64_i32 v[108:109], s[10:11], v102, s12, v[98:99]
	v_lshl_add_u64 v[108:109], v[108:109], 0, v[100:101]
	v_lshl_add_u64 v[108:109], v[108:109], 0, v[32:33]
	s_waitcnt lgkmcnt(0)
	flat_store_dwordx4 v[108:109], v[104:107]
	ds_read_b32 v102, v137 offset:128
	s_waitcnt lgkmcnt(0)
	v_mul_f32_e64 v82, v82, v102
	v_mul_f32_e64 v83, v83, v102
	s_nop 0
	v_mul_f32_e32 v104, 0xbfb8aa3b, v82
	v_mul_f32_e32 v105, 0xbfb8aa3b, v83
	v_exp_f32_e32 v104, v104
	v_exp_f32_e32 v105, v105
	v_mul_f32_e64 v66, v66, v102
	v_mul_f32_e64 v67, v67, v102
	v_mul_f32_e64 v68, v68, v102
	v_mul_f32_e64 v69, v69, v102
	v_add_f32_e32 v104, 1.0, v104
	v_add_f32_e32 v105, 1.0, v105
	v_rcp_f32_e32 v104, v104
	v_rcp_f32_e32 v105, v105
	v_mul_f32_e64 v70, v70, v102
	v_mul_f32_e64 v71, v71, v102
	v_mul_f32_e64 v72, v72, v102
	v_mul_f32_e64 v73, v73, v102
	v_mul_f32_e64 v82, v82, v104
	v_mul_f32_e64 v83, v83, v105
	s_nop 0
	v_mul_f32_e64 v66, v66, v82
	v_mul_f32_e64 v67, v67, v83
	v_mul_f32_e64 v82, v84, v102
	v_mul_f32_e64 v83, v85, v102
	v_cvt_pk_bf16_f32 v66, v66, v67
	v_mul_f32_e32 v84, 0xbfb8aa3b, v82
	v_mul_f32_e32 v85, 0xbfb8aa3b, v83
	v_exp_f32_e32 v84, v84
	v_exp_f32_e32 v85, v85
	v_add_f32_e32 v84, 1.0, v84
	v_add_f32_e32 v85, 1.0, v85
	v_rcp_f32_e32 v84, v84
	v_rcp_f32_e32 v85, v85
	s_nop 0
	v_mul_f32_e64 v82, v82, v84
	v_mul_f32_e64 v83, v83, v85
	s_nop 0
	v_mul_f32_e64 v68, v68, v82
	v_mul_f32_e64 v69, v69, v83
	s_nop 0
	v_cvt_pk_bf16_f32 v67, v68, v69
	ds_write_b64 v135, v[66:67]
	v_mul_f32_e64 v66, v86, v102
	v_mul_f32_e64 v67, v87, v102
	s_nop 0
	v_mul_f32_e32 v68, 0xbfb8aa3b, v66
	v_mul_f32_e32 v69, 0xbfb8aa3b, v67
	v_exp_f32_e32 v68, v68
	v_exp_f32_e32 v69, v69
	v_add_f32_e32 v68, 1.0, v68
	v_add_f32_e32 v69, 1.0, v69
	v_rcp_f32_e32 v68, v68
	v_rcp_f32_e32 v69, v69
	s_nop 0
	v_mul_f32_e64 v66, v66, v68
	v_mul_f32_e64 v67, v67, v69
	v_mul_f32_e64 v68, v88, v102
	v_mul_f32_e64 v69, v89, v102
	v_mul_f32_e64 v66, v70, v66
	v_mul_f32_e64 v67, v71, v67
	v_mul_f32_e32 v70, 0xbfb8aa3b, v68
	v_mul_f32_e32 v71, 0xbfb8aa3b, v69
	v_exp_f32_e32 v70, v70
	v_exp_f32_e32 v71, v71
	v_cvt_pk_bf16_f32 v66, v66, v67
	v_add_f32_e32 v70, 1.0, v70
	v_add_f32_e32 v71, 1.0, v71
	v_rcp_f32_e32 v70, v70
	v_rcp_f32_e32 v71, v71
	s_nop 0
	v_mul_f32_e64 v68, v68, v70
	v_mul_f32_e64 v69, v69, v71
	s_nop 0
	v_mul_f32_e64 v68, v72, v68
	v_mul_f32_e64 v69, v73, v69
	v_mul_f32_e64 v70, v74, v102
	v_mul_f32_e64 v71, v75, v102
	v_cvt_pk_bf16_f32 v67, v68, v69
	ds_write_b64 v135, v[66:67] offset:16
	v_mul_f32_e64 v66, v90, v102
	v_mul_f32_e64 v67, v91, v102
	v_mul_f32_e64 v72, v76, v102
	v_mul_f32_e64 v73, v77, v102
	v_mul_f32_e32 v68, 0xbfb8aa3b, v66
	v_mul_f32_e32 v69, 0xbfb8aa3b, v67
	v_exp_f32_e32 v68, v68
	v_exp_f32_e32 v69, v69
	v_add_f32_e32 v68, 1.0, v68
	v_add_f32_e32 v69, 1.0, v69
	v_rcp_f32_e32 v68, v68
	v_rcp_f32_e32 v69, v69
	s_nop 0
	v_mul_f32_e64 v66, v66, v68
	v_mul_f32_e64 v67, v67, v69
	v_mul_f32_e64 v68, v92, v102
	v_mul_f32_e64 v69, v93, v102
	v_mul_f32_e64 v66, v70, v66
	v_mul_f32_e64 v67, v71, v67
	v_mul_f32_e32 v70, 0xbfb8aa3b, v68
	v_mul_f32_e32 v71, 0xbfb8aa3b, v69
	v_exp_f32_e32 v70, v70
	v_exp_f32_e32 v71, v71
	v_cvt_pk_bf16_f32 v66, v66, v67
	v_add_f32_e32 v70, 1.0, v70
	v_add_f32_e32 v71, 1.0, v71
	v_rcp_f32_e32 v70, v70
	v_rcp_f32_e32 v71, v71
	s_nop 0
	v_mul_f32_e64 v68, v68, v70
	v_mul_f32_e64 v69, v69, v71
	s_nop 0
	v_mul_f32_e64 v68, v72, v68
	v_mul_f32_e64 v69, v73, v69
	v_mul_f32_e64 v70, v78, v102
	v_mul_f32_e64 v71, v79, v102
	v_cvt_pk_bf16_f32 v67, v68, v69
	ds_write_b64 v135, v[66:67] offset:32
	v_mul_f32_e64 v66, v94, v102
	v_mul_f32_e64 v67, v95, v102
	v_mul_f32_e64 v72, v80, v102
	v_mul_f32_e64 v73, v81, v102
	v_mul_f32_e32 v68, 0xbfb8aa3b, v66
	v_mul_f32_e32 v69, 0xbfb8aa3b, v67
	v_exp_f32_e32 v68, v68
	v_exp_f32_e32 v69, v69
	v_add_f32_e32 v68, 1.0, v68
	v_add_f32_e32 v69, 1.0, v69
	v_rcp_f32_e32 v68, v68
	v_rcp_f32_e32 v69, v69
	s_nop 0
	v_mul_f32_e64 v66, v66, v68
	v_mul_f32_e64 v67, v67, v69
	v_mul_f32_e64 v68, v96, v102
	v_mul_f32_e64 v69, v97, v102
	v_mul_f32_e64 v66, v70, v66
	v_mul_f32_e64 v67, v71, v67
	v_mul_f32_e32 v70, 0xbfb8aa3b, v68
	v_mul_f32_e32 v71, 0xbfb8aa3b, v69
	v_exp_f32_e32 v70, v70
	v_exp_f32_e32 v71, v71
	v_cvt_pk_bf16_f32 v66, v66, v67
	v_add_f32_e32 v70, 1.0, v70
	v_add_f32_e32 v71, 1.0, v71
	v_rcp_f32_e32 v70, v70
	v_rcp_f32_e32 v71, v71
	s_nop 0
	v_mul_f32_e64 v68, v68, v70
	v_mul_f32_e64 v69, v69, v71
	s_nop 0
	v_mul_f32_e64 v68, v72, v68
	v_mul_f32_e64 v69, v73, v69
	v_or_b32_e32 v72, 32, v133
	v_cvt_pk_bf16_f32 v67, v68, v69
	ds_write_b64 v135, v[66:67] offset:48
	ds_read_b128 v[66:69], v136
	v_or_b32_e32 v70, v72, v134
	v_mad_i64_i32 v[70:71], s[10:11], v70, s12, v[98:99]
	v_lshl_add_u64 v[70:71], v[70:71], 0, v[100:101]
	v_lshl_add_u64 v[70:71], v[70:71], 0, v[32:33]
	s_waitcnt lgkmcnt(0)
; DI u32x2 pack4(float a, float b, float c, float d) { u32x2 w; w.x = pack2(a, b); w.y = pack2(c, d); return w; }
;   DI void operator()(const f32x16 (&acc)[4][2], bool vt, int row0, int col0, int r, int h, const float* sR, float* stage) const {
;     bf16_t* st = (bf16_t*)stage;
;     const int lane = h * 32 + r;
; #pragma unroll
;     for (int mi = 0; mi < 4; ++mi) {
;       const float rv = sR[mi * 32 + r];
; #pragma unroll
;       for (int g = 0; g < 4; ++g) {
;         float o[4];
; #pragma unroll
;         for (int q = 0; q < 4; ++q) {
;           const float gt = acc[mi][0][4 * g + q] * rv, up = acc[mi][1][4 * g + q] * rv;
;           o[q] = gt * __builtin_amdgcn_rcpf(1.f + __expf(-gt)) * up;
;         }
;         *(u32x2*)(st + r * 40 + 8 * g + 4 * h) = pack4(o[0], o[1], o[2], o[3]);
;       }
; #pragma unroll
;       for (int j = 0; j < 2; ++j) {
;         const int rr = j * 16 + (lane >> 2), cc = (lane & 3) * 8;
;         const u32x4 v = *(const u32x4*)(st + rr * 40 + cc);
;         *(u32x4*)(act + (size_t)(row0 + mi * 32 + rr) * LDF + (col0 >> 1) + cc) = v;
;       }
;     }
	flat_store_dwordx4 v[70:71], v[66:69]
	ds_read_b128 v[66:69], v136 offset:1280
	v_or_b32_e32 v70, v72, v103
	v_mad_i64_i32 v[70:71], s[10:11], v70, s12, v[98:99]
	v_lshl_add_u64 v[70:71], v[70:71], 0, v[100:101]
	v_lshl_add_u64 v[70:71], v[70:71], 0, v[32:33]
	s_waitcnt lgkmcnt(0)
	flat_store_dwordx4 v[70:71], v[66:69]
	ds_read_b32 v66, v137 offset:256
	s_waitcnt lgkmcnt(0)
	v_mul_f32_e64 v50, v50, v66
	v_mul_f32_e64 v51, v51, v66
	s_nop 0
	v_mul_f32_e32 v67, 0xbfb8aa3b, v50
	v_exp_f32_e32 v67, v67
	s_nop 0
	v_add_f32_e32 v67, 1.0, v67
	v_rcp_f32_e32 v68, v67
	v_mul_f32_e64 v34, v34, v66
	v_mul_f32_e64 v35, v35, v66
	v_mul_f32_e32 v67, 0xbfb8aa3b, v51
	v_exp_f32_e32 v67, v67
	s_nop 0
	v_add_f32_e32 v67, 1.0, v67
	v_rcp_f32_e32 v69, v67
	v_mul_f32_e64 v36, v36, v66
	v_mul_f32_e64 v37, v37, v66
	v_mul_f32_e64 v38, v38, v66
	v_mul_f32_e64 v39, v39, v66
	v_mul_f32_e64 v40, v40, v66
	v_mul_f32_e64 v41, v41, v66
	v_mul_f32_e64 v50, v50, v68
	v_mul_f32_e64 v51, v51, v69
	s_nop 0
	v_mul_f32_e64 v34, v34, v50
	v_mul_f32_e64 v35, v35, v51
	v_mul_f32_e64 v50, v52, v66
	v_mul_f32_e64 v51, v53, v66
	v_cvt_pk_bf16_f32 v34, v34, v35
	v_mul_f32_e32 v52, 0xbfb8aa3b, v50
	v_mul_f32_e32 v53, 0xbfb8aa3b, v51
	v_exp_f32_e32 v52, v52
	v_exp_f32_e32 v53, v53
	v_add_f32_e32 v52, 1.0, v52
	v_add_f32_e32 v53, 1.0, v53
	v_rcp_f32_e32 v52, v52
	v_rcp_f32_e32 v53, v53
	s_nop 0
	v_mul_f32_e64 v50, v50, v52
	v_mul_f32_e64 v51, v51, v53
	s_nop 0
	v_mul_f32_e64 v36, v36, v50
	v_mul_f32_e64 v37, v37, v51
	s_nop 0
	v_cvt_pk_bf16_f32 v35, v36, v37
	ds_write_b64 v135, v[34:35]
	v_mul_f32_e64 v34, v54, v66
	v_mul_f32_e64 v35, v55, v66
	s_nop 0
	v_mul_f32_e32 v36, 0xbfb8aa3b, v34
	v_mul_f32_e32 v37, 0xbfb8aa3b, v35
	v_exp_f32_e32 v36, v36
	v_exp_f32_e32 v37, v37
	v_add_f32_e32 v36, 1.0, v36
	v_add_f32_e32 v37, 1.0, v37
	v_rcp_f32_e32 v36, v36
	v_rcp_f32_e32 v37, v37
	s_nop 0
	v_mul_f32_e64 v34, v34, v36
	v_mul_f32_e64 v35, v35, v37
	v_mul_f32_e64 v36, v56, v66
	v_mul_f32_e64 v37, v57, v66
	v_mul_f32_e64 v34, v38, v34
	v_mul_f32_e64 v35, v39, v35
	v_mul_f32_e32 v38, 0xbfb8aa3b, v36
	v_mul_f32_e32 v39, 0xbfb8aa3b, v37
	v_exp_f32_e32 v38, v38
	v_exp_f32_e32 v39, v39
	v_cvt_pk_bf16_f32 v34, v34, v35
	v_add_f32_e32 v38, 1.0, v38
	v_add_f32_e32 v39, 1.0, v39
	v_rcp_f32_e32 v38, v38
	v_rcp_f32_e32 v39, v39
	s_nop 0
	v_mul_f32_e64 v36, v36, v38
	v_mul_f32_e64 v37, v37, v39
	s_nop 0
	v_mul_f32_e64 v36, v40, v36
	v_mul_f32_e64 v37, v41, v37
	v_mul_f32_e64 v38, v42, v66
	v_mul_f32_e64 v39, v43, v66
	v_cvt_pk_bf16_f32 v35, v36, v37
	ds_write_b64 v135, v[34:35] offset:16
	v_mul_f32_e64 v34, v58, v66
	v_mul_f32_e64 v35, v59, v66
	v_mul_f32_e64 v40, v44, v66
	v_mul_f32_e64 v41, v45, v66
	v_mul_f32_e32 v36, 0xbfb8aa3b, v34
	v_mul_f32_e32 v37, 0xbfb8aa3b, v35
	v_exp_f32_e32 v36, v36
	v_exp_f32_e32 v37, v37
	v_add_f32_e32 v36, 1.0, v36
	v_add_f32_e32 v37, 1.0, v37
	v_rcp_f32_e32 v36, v36
	v_rcp_f32_e32 v37, v37
	s_nop 0
	v_mul_f32_e64 v34, v34, v36
	v_mul_f32_e64 v35, v35, v37
	v_mul_f32_e64 v36, v60, v66
	v_mul_f32_e64 v37, v61, v66
	v_mul_f32_e64 v34, v38, v34
	v_mul_f32_e64 v35, v39, v35
	v_mul_f32_e32 v38, 0xbfb8aa3b, v36
	v_mul_f32_e32 v39, 0xbfb8aa3b, v37
	v_exp_f32_e32 v38, v38
	v_exp_f32_e32 v39, v39
	v_cvt_pk_bf16_f32 v34, v34, v35
	v_add_f32_e32 v38, 1.0, v38
	v_add_f32_e32 v39, 1.0, v39
	v_rcp_f32_e32 v38, v38
	v_rcp_f32_e32 v39, v39
	s_nop 0
	v_mul_f32_e64 v36, v36, v38
	v_mul_f32_e64 v37, v37, v39
	s_nop 0
	v_mul_f32_e64 v36, v40, v36
	v_mul_f32_e64 v37, v41, v37
	v_mul_f32_e64 v38, v46, v66
	v_mul_f32_e64 v39, v47, v66
	v_cvt_pk_bf16_f32 v35, v36, v37
	ds_write_b64 v135, v[34:35] offset:32
	v_mul_f32_e64 v34, v62, v66
	v_mul_f32_e64 v35, v63, v66
	v_mul_f32_e64 v40, v48, v66
	v_mul_f32_e64 v41, v49, v66
	v_mul_f32_e32 v36, 0xbfb8aa3b, v34
	v_mul_f32_e32 v37, 0xbfb8aa3b, v35
	v_exp_f32_e32 v36, v36
	v_exp_f32_e32 v37, v37
	v_add_f32_e32 v36, 1.0, v36
	v_add_f32_e32 v37, 1.0, v37
	v_rcp_f32_e32 v36, v36
	v_rcp_f32_e32 v37, v37
	s_nop 0
	v_mul_f32_e64 v34, v34, v36
	v_mul_f32_e64 v35, v35, v37
	v_mul_f32_e64 v36, v64, v66
	v_mul_f32_e64 v37, v65, v66
	v_mul_f32_e64 v34, v38, v34
	v_mul_f32_e64 v35, v39, v35
	v_mul_f32_e32 v38, 0xbfb8aa3b, v36
	v_mul_f32_e32 v39, 0xbfb8aa3b, v37
	v_exp_f32_e32 v38, v38
	v_exp_f32_e32 v39, v39
	v_cvt_pk_bf16_f32 v34, v34, v35
	v_add_f32_e32 v38, 1.0, v38
	v_add_f32_e32 v39, 1.0, v39
	v_rcp_f32_e32 v38, v38
	v_rcp_f32_e32 v39, v39
	s_nop 0
	v_mul_f32_e64 v36, v36, v38
	v_mul_f32_e64 v37, v37, v39
	s_nop 0
	v_mul_f32_e64 v36, v40, v36
	v_mul_f32_e64 v37, v41, v37
	v_or_b32_e32 v40, 64, v133
	v_cvt_pk_bf16_f32 v35, v36, v37
	ds_write_b64 v135, v[34:35] offset:48
	ds_read_b128 v[34:37], v136
	v_or_b32_e32 v38, v40, v134
	v_mad_i64_i32 v[38:39], s[10:11], v38, s12, v[98:99]
	v_lshl_add_u64 v[38:39], v[38:39], 0, v[100:101]
	v_lshl_add_u64 v[38:39], v[38:39], 0, v[32:33]
	s_waitcnt lgkmcnt(0)
; DI u32x2 pack4(float a, float b, float c, float d) { u32x2 w; w.x = pack2(a, b); w.y = pack2(c, d); return w; }
;     ...
;   if (Epi::STAGED) __syncthreads();
;   float* stg = Epi::CHAIN ? (float*)(smem + st_last * (STG * 2) + wid * 6144) : (float*)smem + wid * 2176;
;   if (pm == 0) epi(acc, vt, m0 + wm * 128, n0 + wn * 64, r, h, sR + wm * 128, stg);
;   __syncthreads();
;   DI void operator()(const f32x16 (&acc)[4][2], bool vt, int row0, int col0, int r, int h, const float* sR, float* stage) const {
;     bf16_t* st = (bf16_t*)stage;
;     const int lane = h * 32 + r;
; #pragma unroll
;     for (int mi = 0; mi < 4; ++mi) {
;       const float rv = sR[mi * 32 + r];
; #pragma unroll
;       for (int g = 0; g < 4; ++g) {
;         float o[4];
; #pragma unroll
;         for (int q = 0; q < 4; ++q) {
;           const float gt = acc[mi][0][4 * g + q] * rv, up = acc[mi][1][4 * g + q] * rv;
;           o[q] = gt * __builtin_amdgcn_rcpf(1.f + __expf(-gt)) * up;
;         }
;         *(u32x2*)(st + r * 40 + 8 * g + 4 * h) = pack4(o[0], o[1], o[2], o[3]);
;       }
; #pragma unroll
;       for (int j = 0; j < 2; ++j) {
;         const int rr = j * 16 + (lane >> 2), cc = (lane & 3) * 8;
;         const u32x4 v = *(const u32x4*)(st + rr * 40 + cc);
;         *(u32x4*)(act + (size_t)(row0 + mi * 32 + rr) * LDF + (col0 >> 1) + cc) = v;
;       }
;     }
	flat_store_dwordx4 v[38:39], v[34:37]
	ds_read_b128 v[34:37], v136 offset:1280
	v_or_b32_e32 v38, v40, v103
	v_mad_i64_i32 v[38:39], s[10:11], v38, s12, v[98:99]
	v_lshl_add_u64 v[38:39], v[38:39], 0, v[100:101]
	v_lshl_add_u64 v[38:39], v[38:39], 0, v[32:33]
	s_waitcnt lgkmcnt(0)
	flat_store_dwordx4 v[38:39], v[34:37]
	ds_read_b32 v34, v137 offset:384
	s_waitcnt lgkmcnt(0)
	v_mul_f32_e64 v16, v16, v34
	v_mul_f32_e64 v17, v17, v34
	s_nop 0
	v_mul_f32_e32 v35, 0xbfb8aa3b, v16
	v_exp_f32_e32 v35, v35
	s_nop 0
	v_add_f32_e32 v35, 1.0, v35
	v_rcp_f32_e32 v36, v35
	v_mul_f32_e64 v0, v0, v34
	v_mul_f32_e64 v1, v1, v34
	v_mul_f32_e32 v35, 0xbfb8aa3b, v17
	v_exp_f32_e32 v35, v35
	s_nop 0
	v_add_f32_e32 v35, 1.0, v35
	v_rcp_f32_e32 v37, v35
	v_mul_f32_e64 v2, v2, v34
	v_mul_f32_e64 v3, v3, v34
	v_mul_f32_e64 v4, v4, v34
	v_mul_f32_e64 v5, v5, v34
	v_mul_f32_e64 v6, v6, v34
	v_mul_f32_e64 v7, v7, v34
	v_mul_f32_e64 v16, v16, v36
	v_mul_f32_e64 v17, v17, v37
	s_nop 0
	v_mul_f32_e64 v0, v0, v16
	v_mul_f32_e64 v1, v1, v17
	v_mul_f32_e64 v16, v18, v34
	v_mul_f32_e64 v17, v19, v34
	v_cvt_pk_bf16_f32 v0, v0, v1
	v_mul_f32_e32 v18, 0xbfb8aa3b, v16
	v_mul_f32_e32 v19, 0xbfb8aa3b, v17
	v_exp_f32_e32 v18, v18
	v_exp_f32_e32 v19, v19
	v_add_f32_e32 v18, 1.0, v18
	v_add_f32_e32 v19, 1.0, v19
	v_rcp_f32_e32 v18, v18
	v_rcp_f32_e32 v19, v19
	s_nop 0
	v_mul_f32_e64 v16, v16, v18
	v_mul_f32_e64 v17, v17, v19
	s_nop 0
	v_mul_f32_e64 v2, v2, v16
	v_mul_f32_e64 v3, v3, v17
	s_nop 0
	v_cvt_pk_bf16_f32 v1, v2, v3
	ds_write_b64 v135, v[0:1]
	v_mul_f32_e64 v0, v20, v34
	v_mul_f32_e64 v1, v21, v34
	s_nop 0
	v_mul_f32_e32 v2, 0xbfb8aa3b, v0
	v_mul_f32_e32 v3, 0xbfb8aa3b, v1
	v_exp_f32_e32 v2, v2
	v_exp_f32_e32 v3, v3
	v_add_f32_e32 v2, 1.0, v2
	v_add_f32_e32 v3, 1.0, v3
	v_rcp_f32_e32 v2, v2
	v_rcp_f32_e32 v3, v3
	s_nop 0
	v_mul_f32_e64 v0, v0, v2
	v_mul_f32_e64 v1, v1, v3
	v_mul_f32_e64 v2, v22, v34
	v_mul_f32_e64 v3, v23, v34
	v_mul_f32_e64 v0, v4, v0
	v_mul_f32_e64 v1, v5, v1
	v_mul_f32_e32 v4, 0xbfb8aa3b, v2
	v_mul_f32_e32 v5, 0xbfb8aa3b, v3
	v_exp_f32_e32 v4, v4
	v_exp_f32_e32 v5, v5
	v_cvt_pk_bf16_f32 v0, v0, v1
	v_add_f32_e32 v4, 1.0, v4
	v_add_f32_e32 v5, 1.0, v5
	v_rcp_f32_e32 v4, v4
	v_rcp_f32_e32 v5, v5
	s_nop 0
	v_mul_f32_e64 v2, v2, v4
	v_mul_f32_e64 v3, v3, v5
	s_nop 0
	v_mul_f32_e64 v2, v6, v2
	v_mul_f32_e64 v3, v7, v3
	v_mul_f32_e64 v4, v8, v34
	v_mul_f32_e64 v5, v9, v34
	v_cvt_pk_bf16_f32 v1, v2, v3
	ds_write_b64 v135, v[0:1] offset:16
	v_mul_f32_e64 v0, v24, v34
	v_mul_f32_e64 v1, v25, v34
	v_mul_f32_e64 v6, v10, v34
	v_mul_f32_e64 v7, v11, v34
	v_mul_f32_e32 v2, 0xbfb8aa3b, v0
	v_mul_f32_e32 v3, 0xbfb8aa3b, v1
	v_exp_f32_e32 v2, v2
	v_exp_f32_e32 v3, v3
	v_add_f32_e32 v2, 1.0, v2
	v_add_f32_e32 v3, 1.0, v3
	v_rcp_f32_e32 v2, v2
	v_rcp_f32_e32 v3, v3
	s_nop 0
	v_mul_f32_e64 v0, v0, v2
	v_mul_f32_e64 v1, v1, v3
	v_mul_f32_e64 v2, v26, v34
	v_mul_f32_e64 v3, v27, v34
	v_mul_f32_e64 v0, v4, v0
	v_mul_f32_e64 v1, v5, v1
	v_mul_f32_e32 v4, 0xbfb8aa3b, v2
	v_mul_f32_e32 v5, 0xbfb8aa3b, v3
	v_exp_f32_e32 v4, v4
	v_exp_f32_e32 v5, v5
	v_cvt_pk_bf16_f32 v0, v0, v1
	v_add_f32_e32 v4, 1.0, v4
	v_add_f32_e32 v5, 1.0, v5
	v_rcp_f32_e32 v4, v4
	v_rcp_f32_e32 v5, v5
	s_nop 0
	v_mul_f32_e64 v2, v2, v4
	v_mul_f32_e64 v3, v3, v5
	s_nop 0
	v_mul_f32_e64 v2, v6, v2
	v_mul_f32_e64 v3, v7, v3
	v_mul_f32_e64 v4, v12, v34
	v_mul_f32_e64 v5, v13, v34
	v_cvt_pk_bf16_f32 v1, v2, v3
	ds_write_b64 v135, v[0:1] offset:32
	v_mul_f32_e64 v0, v28, v34
	v_mul_f32_e64 v1, v29, v34
	v_mul_f32_e64 v6, v14, v34
	v_mul_f32_e64 v7, v15, v34
	v_mul_f32_e32 v2, 0xbfb8aa3b, v0
	v_mul_f32_e32 v3, 0xbfb8aa3b, v1
	v_exp_f32_e32 v2, v2
	v_exp_f32_e32 v3, v3
	v_add_f32_e32 v2, 1.0, v2
	v_add_f32_e32 v3, 1.0, v3
	v_rcp_f32_e32 v2, v2
	v_rcp_f32_e32 v3, v3
	s_nop 0
	v_mul_f32_e64 v0, v0, v2
	v_mul_f32_e64 v1, v1, v3
	v_mul_f32_e64 v2, v30, v34
	v_mul_f32_e64 v3, v31, v34
	v_mul_f32_e64 v0, v4, v0
	v_mul_f32_e64 v1, v5, v1
	v_mul_f32_e32 v4, 0xbfb8aa3b, v2
	v_mul_f32_e32 v5, 0xbfb8aa3b, v3
	v_exp_f32_e32 v4, v4
	v_exp_f32_e32 v5, v5
	v_cvt_pk_bf16_f32 v0, v0, v1
	v_add_f32_e32 v4, 1.0, v4
	v_add_f32_e32 v5, 1.0, v5
	v_rcp_f32_e32 v4, v4
	v_rcp_f32_e32 v5, v5
	s_nop 0
	v_mul_f32_e64 v2, v2, v4
	v_mul_f32_e64 v3, v3, v5
	s_nop 0
	v_mul_f32_e64 v2, v6, v2
	v_mul_f32_e64 v3, v7, v3
	v_or_b32_e32 v6, 0x60, v133
	v_cvt_pk_bf16_f32 v1, v2, v3
	ds_write_b64 v135, v[0:1] offset:48
	ds_read_b128 v[0:3], v136
	v_or_b32_e32 v4, v6, v134
	v_mad_i64_i32 v[4:5], s[10:11], v4, s12, v[98:99]
	v_lshl_add_u64 v[4:5], v[4:5], 0, v[100:101]
	v_lshl_add_u64 v[4:5], v[4:5], 0, v[32:33]
	s_waitcnt lgkmcnt(0)
	flat_store_dwordx4 v[4:5], v[0:3]
	ds_read_b128 v[0:3], v136 offset:1280
	v_or_b32_e32 v4, v6, v103
	v_mad_i64_i32 v[4:5], s[10:11], v4, s12, v[98:99]
	v_lshl_add_u64 v[4:5], v[4:5], 0, v[100:101]
	v_lshl_add_u64 v[4:5], v[4:5], 0, v[32:33]
	s_waitcnt lgkmcnt(0)
	flat_store_dwordx4 v[4:5], v[0:3]
	s_waitcnt lgkmcnt(0)
	s_barrier
	s_cbranch_vccz .LBB0_1266

;     ...
;   if (ssq) {
;     const f32x4* sp = (const f32x4*)(ssq + (size_t)(m0 + tid) * 16);
;     const f32x4 a = sp[0], b = sp[1], c = sp[2], d = sp[3];
;     const float tot = ((a.x + a.y) + (a.z + a.w)) + ((b.x + b.y) + (b.z + b.w)) + ((c.x + c.y) + (c.z + c.w)) + ((d.x + d.y) + (d.z + d.w));
;     sR[tid] = rsqrtf(tot * (1.f / DM) + 1e-6f);
;   }
;   __syncthreads();
;     ...
;     const int xcd = t & 7, j = t >> 3;
;     const int grp = j / (8 * nN), jj = j % (8 * nN);
;     const int tm = xcd * band + grp * 8 + (jj & 7), tn = jj >> 3;
.LBB0_1254:
	s_ashr_i32 s14, s13, 3
	s_mul_hi_i32 s15, s14, 0x2e8ba2e9
	s_lshr_b32 s25, s15, 31
	s_ashr_i32 s28, s15, 6
	s_add_i32 s28, s28, s25
	s_mul_i32 s15, s28, 0x160
	s_sub_i32 s27, s14, s15
	s_and_b32 s13, s13, 7
	s_add_i32 s13, s28, s13
	s_lshl_b32 s14, s27, 8
	s_lshl_b32 s13, s13, 11
	s_and_b32 s29, s14, 0x700
	s_waitcnt vmcnt(0)
	v_mov_b32_e32 v152, v242
	s_or_b32 s25, s13, s29
	s_cmp_gt_i32 s12, -1
	v_add_u32_e32 v0, s25, v152
	v_ashrrev_i32_e32 v1, 31, v0
	v_lshlrev_b64 v[0:1], 6, v[0:1]
	v_lshl_add_u64 v[12:13], s[0:1], 0, v[0:1]
	flat_load_dwordx4 v[0:3], v[12:13]
	flat_load_dwordx4 v[4:7], v[12:13] offset:16
	flat_load_dwordx4 v[8:11], v[12:13] offset:32
	s_nop 0
	flat_load_dwordx4 v[12:15], v[12:13] offset:48
	s_cselect_b64 s[14:15], -1, 0
	s_cmp_lt_i32 s12, 0
	s_waitcnt vmcnt(0) lgkmcnt(0)
	v_mov_b32_e32 v16, v1
	v_mov_b32_e32 v17, v2
	v_mov_b32_e32 v1, v3
	v_mov_b32_e32 v2, v5
	v_mov_b32_e32 v3, v6
	v_mov_b32_e32 v5, v7
	v_add_f32_e64 v0, v16, v0
	v_add_f32_e64 v1, v17, v1
	v_add_f32_e64 v2, v2, v4
	v_add_f32_e64 v3, v3, v5
	v_pk_add_f32 v[0:1], v[0:1], v[0:1] op_sel:[0,1] op_sel_hi:[1,0]
	v_pk_add_f32 v[2:3], v[2:3], v[2:3] op_sel:[0,1] op_sel_hi:[1,0]
	v_add_f32_e32 v4, v8, v9
	v_add_f32_e32 v6, v10, v11
	v_mov_b32_e32 v1, v12
	v_mov_b32_e32 v3, v13
	v_mov_b32_e32 v5, v14
	v_mov_b32_e32 v7, v15
	v_add_f32_e64 v0, v0, v2
	v_add_f32_e64 v1, v1, v3
	v_add_f32_e64 v2, v4, v6
	v_add_f32_e64 v3, v5, v7
	s_nop 0
	v_add_f32_e64 v0, v0, v2
	v_add_f32_e64 v1, v1, v3
	s_nop 0
	v_add_f32_e32 v0, v0, v1
	v_fmamk_f32 v0, v0, 0x3a800000, v240
	v_cmp_gt_f32_e32 vcc, s79, v0
	v_mul_f32_e32 v1, 0x4b800000, v0
	s_nop 0
	v_cndmask_b32_e32 v0, v0, v1, vcc
	v_rsq_f32_e32 v0, v0
	s_nop 0
	v_mul_f32_e32 v1, 0x45800000, v0
	v_cndmask_b32_e32 v0, v0, v1, vcc
	v_lshl_add_u32 v1, v152, 2, v210
	ds_write_b32 v1, v0
	s_waitcnt lgkmcnt(0)
	s_barrier
	s_cbranch_scc1 .LBB0_1256
	s_lshl_b32 s13, s12, 8
	s_mul_i32 s12, s12, 0x88000
	s_mul_hi_u32 s13, s13, 0x880
	s_add_u32 s12, s16, s12
	s_addc_u32 s13, s17, s13
	s_branch .LBB0_1257

; DI int otid() { int t = threadIdx.x; asm volatile("" : "+v"(t)); return t; }
; DI void final_phase(float* xio, const float* g) {
;   const int tidx = otid(), lane = tidx & 63, gw = blockIdx.x * 4 + (tidx >> 6), nw = gridDim.x * 4;
;   for (int row = gw; row < M; row += nw) {
;     float* xr = xio + (size_t)row * DM;
;     f32x4 v[4]; float ss = 0.f;
; #pragma unroll
;     for (int i = 0; i < 4; ++i) { v[i] = *(const f32x4*)(xr + (i * 64 + lane) * 4); ss += v[i].x * v[i].x + v[i].y * v[i].y + v[i].z * v[i].z + v[i].w * v[i].w; }
; #pragma unroll
;     for (int o = 1; o < 64; o <<= 1) ss += __shfl_xor(ss, o);
;     const float rinv = rsqrtf(ss * (1.f / DM) + 1e-6f);
; #pragma unroll
;     for (int i = 0; i < 4; ++i) {
;       const f32x4 gg = *(const f32x4*)(g + (i * 64 + lane) * 4);
;       f32x4 o; o.x = v[i].x * rinv * gg.x; o.y = v[i].y * rinv * gg.y; o.z = v[i].z * rinv * gg.z; o.w = v[i].w * rinv * gg.w;
;       *(f32x4*)(xr + (i * 64 + lane) * 4) = o;
;     }
;   }
; }
.LBB0_1425:
	flat_load_dwordx4 v[12:15], v[4:5]
	flat_load_dwordx4 v[16:19], v[4:5] offset:1024
	flat_load_dwordx4 v[20:23], v[4:5] offset:2048
	flat_load_dwordx4 v[24:27], v[4:5] offset:3072
	global_load_dwordx4 v[28:31], v[2:3], off
	v_add_u32_e32 v0, s0, v0
	s_waitcnt vmcnt(0) lgkmcnt(0)
	v_mov_b32_e32 v34, v13
	v_mov_b32_e32 v35, v17
	v_mov_b32_e32 v32, v12
	v_mov_b32_e32 v33, v16
	v_mov_b32_e32 v42, v21
	v_mov_b32_e32 v43, v25
	v_mul_f32_e64 v34, v34, v34
	v_mul_f32_e64 v35, v35, v35
	v_mov_b32_e32 v36, v14
	v_mov_b32_e32 v37, v18
	v_mov_b32_e32 v40, v20
	v_mov_b32_e32 v41, v24
	v_mul_f32_e64 v42, v42, v42
	v_mul_f32_e64 v43, v43, v43
	v_fma_f32 v32, v32, v32, v34
	v_fma_f32 v33, v33, v33, v35
	v_mov_b32_e32 v38, v15
	v_mov_b32_e32 v39, v19
	v_mov_b32_e32 v44, v22
	v_mov_b32_e32 v45, v26
	v_fma_f32 v34, v40, v40, v42
	v_fma_f32 v35, v41, v41, v43
	v_fma_f32 v32, v36, v36, v32
	v_fma_f32 v33, v37, v37, v33
	v_mov_b32_e32 v46, v23
	v_mov_b32_e32 v47, v27
	v_fma_f32 v34, v44, v44, v34
	v_fma_f32 v35, v45, v45, v35
	v_fma_f32 v32, v38, v38, v32
	v_fma_f32 v33, v39, v39, v33
	v_fma_f32 v34, v46, v46, v34
	v_fma_f32 v35, v47, v47, v35
	v_add_f32_e32 v32, v32, v33
	v_add_f32_e32 v32, v32, v34
	v_add_f32_e32 v32, v32, v35
	ds_bpermute_b32 v33, v6, v32
	s_waitcnt lgkmcnt(0)
	v_add_f32_e32 v32, v32, v33
	ds_bpermute_b32 v33, v7, v32
	s_waitcnt lgkmcnt(0)
	v_add_f32_e32 v32, v32, v33
	ds_bpermute_b32 v33, v8, v32
	s_waitcnt lgkmcnt(0)
	v_add_f32_e32 v32, v32, v33
	ds_bpermute_b32 v33, v9, v32
	s_waitcnt lgkmcnt(0)
	v_add_f32_e32 v32, v32, v33
	ds_bpermute_b32 v33, v10, v32
	s_waitcnt lgkmcnt(0)
	v_add_f32_e32 v32, v32, v33
	ds_bpermute_b32 v33, v11, v32
	s_waitcnt lgkmcnt(0)
	v_add_f32_e32 v32, v32, v33
	v_fmamk_f32 v32, v32, 0x3a800000, v1
	v_mul_f32_e32 v33, 0x4b800000, v32
	v_cmp_gt_f32_e32 vcc, s1, v32
	s_nop 1
	v_cndmask_b32_e32 v32, v32, v33, vcc
	v_rsq_f32_e32 v32, v32
	s_nop 0
	v_mul_f32_e32 v33, 0x45800000, v32
	v_cndmask_b32_e32 v32, v32, v33, vcc
	v_mul_f32_e64 v12, v12, v32
	v_mul_f32_e64 v13, v13, v32
	v_mul_f32_e64 v14, v14, v32
	v_mul_f32_e64 v15, v15, v32
	v_mul_f32_e64 v12, v28, v12
	v_mul_f32_e64 v13, v29, v13
	v_mul_f32_e64 v14, v30, v14
	v_mul_f32_e64 v15, v31, v15
	flat_store_dwordx4 v[4:5], v[12:15]
	global_load_dwordx4 v[12:15], v[2:3], off offset:1024
	v_mul_f32_e64 v18, v18, v32
	v_mul_f32_e64 v19, v19, v32
	v_mul_f32_e64 v16, v16, v32
	v_mul_f32_e64 v17, v17, v32
	v_cmp_lt_i32_e32 vcc, s6, v0
	s_or_b64 s[4:5], vcc, s[4:5]
	s_waitcnt vmcnt(0)
	v_mul_f32_e64 v12, v12, v16
	v_mul_f32_e64 v13, v13, v17
	v_mul_f32_e64 v14, v14, v18
	v_mul_f32_e64 v15, v15, v19
	flat_store_dwordx4 v[4:5], v[12:15] offset:1024
	global_load_dwordx4 v[12:15], v[2:3], off offset:2048
	v_mul_f32_e64 v16, v22, v32
	v_mul_f32_e64 v17, v23, v32
	v_mul_f32_e64 v18, v20, v32
	v_mul_f32_e64 v19, v21, v32
	s_waitcnt vmcnt(0)
	v_mul_f32_e64 v14, v14, v16
	v_mul_f32_e64 v15, v15, v17
	v_mul_f32_e64 v12, v12, v18
	v_mul_f32_e64 v13, v13, v19
	flat_store_dwordx4 v[4:5], v[12:15] offset:2048
	global_load_dwordx4 v[12:15], v[2:3], off offset:3072
	v_mul_f32_e64 v16, v26, v32
	v_mul_f32_e64 v17, v27, v32
	v_mul_f32_e64 v18, v24, v32
	v_mul_f32_e64 v19, v25, v32
	s_waitcnt vmcnt(0)
	v_mul_f32_e64 v14, v14, v16
	v_mul_f32_e64 v15, v15, v17
	v_mul_f32_e64 v12, v12, v18
	v_mul_f32_e64 v13, v13, v19
	flat_store_dwordx4 v[4:5], v[12:15] offset:3072
	v_lshl_add_u64 v[4:5], v[4:5], 0, s[2:3]
	s_andn2_b64 exec, exec, s[4:5]
	s_cbranch_execnz .LBB0_1425
